# P6 norm2 loop hand-rewritten with 16B loads + 2-deep prefetch; kv-up epilogue gain loads hoisted; attention pk ops unpacked
# speedup vs baseline: 1.0124x; 1.0124x over previous
; __device__ __forceinline__ unsigned cvt_pk_bf16(float lo, float hi) { unsigned r; asm("v_cvt_pk_bf16_f32 %0, %1, %2" : "=v"(r) : "v"(lo), "v"(hi)); return r; }
;     __device__ __forceinline__ void epi(Acc& acc, const Unit& u, int wr, int wc, int fr, int fq) const {
;     ...
;                     const int head = u.pn * 4 + wc; float s = 0.f;
; #pragma unroll
;                     for (int bj = 0; bj < 2; ++bj)
; #pragma unroll
;                         for (int n = 0; n < 2; ++n) { const f32x4 x = acc[ai][bj][m][n]; s += (x[0] * x[0] + x[1] * x[1]) + (x[2] * x[2] + x[3] * x[3]); }
;                     s += __shfl_xor(s, 16); s += __shfl_xor(s, 32);
;                     const float r2 = rsqrtf(s * (1.f / 64.f) + EPS);
; #pragma unroll
;                     for (int bj = 0; bj < 2; ++bj) { const f32x4 g0 = *(const f32x4*)(kng + bj * 32 + fq * 8), g1 = *(const f32x4*)(kng + bj * 32 + fq * 8 + 4);
;                         const f32x4 a = acc[ai][bj][m][0] * r2 * g0, b = acc[ai][bj][m][1] * r2 * g1;
;                         u32x4 w; w.x = cvt_pk_bf16(a[0], a[1]); w.y = cvt_pk_bf16(a[2], a[3]); w.z = cvt_pk_bf16(b[0], b[1]); w.w = cvt_pk_bf16(b[2], b[3]);
;                         *(u32x4*)(KN + row * 512 + head * 64 + bj * 32 + fq * 8) = w; }
.LBB0_626:
	v_readlane_b32 s80, v238, 20
	v_readlane_b32 s84, v238, 24
	v_readlane_b32 s85, v238, 25
	s_andn2_b64 vcc, exec, s[0:1]
	v_readlane_b32 s81, v238, 21
	v_lshl_add_u64 v[146:147], v[144:145], 2, s[84:85]
	v_readlane_b32 s82, v238, 22
	v_readlane_b32 s83, v238, 23
	v_readlane_b32 s86, v238, 26
	v_readlane_b32 s87, v238, 27
	v_readlane_b32 s88, v238, 28
	v_readlane_b32 s89, v238, 29
	v_readlane_b32 s90, v238, 30
	v_readlane_b32 s91, v238, 31
	v_readlane_b32 s92, v238, 32
	v_readlane_b32 s93, v238, 33
	v_readlane_b32 s94, v238, 34
	v_readlane_b32 s95, v238, 35
	s_cbranch_vccnz .LBB0_628
	global_load_dwordx4 v[190:193], v[146:147], off
	global_load_dwordx4 v[194:197], v[146:147], off offset:16
	global_load_dwordx4 v[198:201], v[146:147], off offset:128
	global_load_dwordx4 v[202:205], v[146:147], off offset:144
	v_pk_mul_f32 v[158:159], v[126:127], v[126:127]
	v_pk_mul_f32 v[160:161], v[124:125], v[124:125]
	v_pk_mul_f32 v[162:163], v[122:123], v[122:123]
	v_pk_mul_f32 v[164:165], v[120:121], v[120:121]
	v_pk_mov_b32 v[170:171], v[160:161], v[158:159] op_sel:[1,0]
	v_mov_b32_e32 v161, v159
	v_pk_mov_b32 v[158:159], v[164:165], v[162:163] op_sel:[1,0]
	v_mov_b32_e32 v165, v163
	v_mul_f32_e32 v169, v112, v112
	v_mul_f32_e32 v166, v117, v117
	v_mul_f32_e32 v168, v119, v119
	v_pk_add_f32 v[160:161], v[170:171], v[160:161]
	v_pk_add_f32 v[158:159], v[158:159], v[164:165]
	v_mul_f32_e32 v172, v113, v113
	v_mul_f32_e32 v173, v114, v114
	v_mul_f32_e32 v174, v115, v115
	v_and_b32_e32 v176, 64, v157
	v_pk_fma_f32 v[162:163], v[116:117], v[116:117], v[166:167] op_sel_hi:[1,1,0]
	v_pk_fma_f32 v[166:167], v[118:119], v[118:119], v[168:169] op_sel_hi:[1,1,0]
	v_pk_add_f32 v[160:161], v[160:161], v[160:161] op_sel:[0,1] op_sel_hi:[1,0]
	v_pk_add_f32 v[158:159], v[158:159], v[158:159] op_sel:[0,1] op_sel_hi:[1,0]
	v_xor_b32_e32 v175, 16, v157
	v_add_u32_e32 v168, 64, v176
	v_mov_b32_e32 v163, v173
	v_mov_b32_e32 v167, v174
	v_mov_b32_e32 v161, v169
	v_mov_b32_e32 v159, v172
	v_cmp_lt_i32_e32 vcc, v175, v168
	v_pk_add_f32 v[162:163], v[162:163], v[166:167]
	v_pk_add_f32 v[158:159], v[160:161], v[158:159]
	v_cndmask_b32_e32 v164, v157, v175, vcc
	v_pk_add_f32 v[158:159], v[158:159], v[162:163]
	v_lshlrev_b32_e32 v164, 2, v164
	v_add_f32_e32 v158, v158, v159
	ds_bpermute_b32 v159, v164, v158
	v_xor_b32_e32 v160, 32, v157
	v_cmp_lt_i32_e32 vcc, v160, v168
	s_lshl_b32 s0, s48, 8
	s_or_b32 s0, s0, s33
	v_cndmask_b32_e32 v160, v157, v160, vcc
	v_lshlrev_b32_e32 v160, 2, v160
	s_waitcnt lgkmcnt(0)
	v_add_f32_e32 v161, v158, v159
	ds_bpermute_b32 v160, v160, v161
	v_lshlrev_b64 v[158:159], 10, v[148:149]
	v_lshl_add_u64 v[158:159], s[4:5], 0, v[158:159]
	s_ashr_i32 s1, s0, 31
	v_lshl_add_u64 v[158:159], s[0:1], 1, v[158:159]
	s_waitcnt lgkmcnt(0)
	v_add_f32_e32 v160, v161, v160
	v_fmamk_f32 v160, v160, 0x3c800000, v156
	v_mul_f32_e32 v161, 0x4b800000, v160
	v_cmp_gt_f32_e32 vcc, s13, v160
	s_nop 1
	v_cndmask_b32_e32 v160, v160, v161, vcc
	v_rsq_f32_e32 v162, v160
	v_lshl_add_u64 v[160:161], v[144:145], 1, v[158:159]
	v_mul_f32_e32 v163, 0x45800000, v162
	v_cndmask_b32_e32 v162, v162, v163, vcc
	v_pk_mul_f32 v[120:121], v[120:121], v[162:163] op_sel_hi:[1,0]
	v_pk_mul_f32 v[122:123], v[122:123], v[162:163] op_sel_hi:[1,0]
	v_pk_mul_f32 v[124:125], v[124:125], v[162:163] op_sel_hi:[1,0]
	v_pk_mul_f32 v[126:127], v[126:127], v[162:163] op_sel_hi:[1,0]
	v_pk_mul_f32 v[116:117], v[116:117], v[162:163] op_sel_hi:[1,0]
	v_pk_mul_f32 v[118:119], v[118:119], v[162:163] op_sel_hi:[1,0]
	v_pk_mul_f32 v[112:113], v[112:113], v[162:163] op_sel_hi:[1,0]
	v_pk_mul_f32 v[114:115], v[114:115], v[162:163] op_sel_hi:[1,0]
	s_waitcnt vmcnt(0)
	v_pk_mul_f32 v[126:127], v[192:193], v[126:127]
	v_pk_mul_f32 v[130:131], v[196:197], v[122:123]
	v_pk_mul_f32 v[122:123], v[194:195], v[120:121]
	v_pk_mul_f32 v[124:125], v[190:191], v[124:125]
	v_cvt_pk_bf16_f32 v121, v126, v127
	v_cvt_pk_bf16_f32 v122, v122, v123
	v_cvt_pk_bf16_f32 v123, v130, v131
	v_lshl_add_u64 v[132:133], v[158:159], 0, 64
	v_cvt_pk_bf16_f32 v120, v124, v125
	global_store_dwordx4 v[160:161], v[120:123], off
	s_nop 0
	v_pk_mul_f32 v[118:119], v[200:201], v[118:119]
	v_pk_mul_f32 v[116:117], v[198:199], v[116:117]
	v_pk_mul_f32 v[114:115], v[204:205], v[114:115]
	v_pk_mul_f32 v[112:113], v[202:203], v[112:113]
	v_cvt_pk_bf16_f32 v128, v116, v117
	v_cvt_pk_bf16_f32 v129, v118, v119
	v_cvt_pk_bf16_f32 v131, v114, v115
	s_nop 0
	v_cvt_pk_bf16_f32 v130, v112, v113

; __device__ __forceinline__ unsigned cvt_pk_bf16(float lo, float hi) { unsigned r; asm("v_cvt_pk_bf16_f32 %0, %1, %2" : "=v"(r) : "v"(lo), "v"(hi)); return r; }
;     __device__ __forceinline__ void epi(Acc& acc, const Unit& u, int wr, int wc, int fr, int fq) const {
;     ...
;                     const int head = u.pn * 4 + wc; float s = 0.f;
; #pragma unroll
;                     for (int bj = 0; bj < 2; ++bj)
; #pragma unroll
;                         for (int n = 0; n < 2; ++n) { const f32x4 x = acc[ai][bj][m][n]; s += (x[0] * x[0] + x[1] * x[1]) + (x[2] * x[2] + x[3] * x[3]); }
;                     s += __shfl_xor(s, 16); s += __shfl_xor(s, 32);
;                     const float r2 = rsqrtf(s * (1.f / 64.f) + EPS);
; #pragma unroll
;                     for (int bj = 0; bj < 2; ++bj) { const f32x4 g0 = *(const f32x4*)(kng + bj * 32 + fq * 8), g1 = *(const f32x4*)(kng + bj * 32 + fq * 8 + 4);
;                         const f32x4 a = acc[ai][bj][m][0] * r2 * g0, b = acc[ai][bj][m][1] * r2 * g1;
;                         u32x4 w; w.x = cvt_pk_bf16(a[0], a[1]); w.y = cvt_pk_bf16(a[2], a[3]); w.z = cvt_pk_bf16(b[0], b[1]); w.w = cvt_pk_bf16(b[2], b[3]);
;                         *(u32x4*)(KN + row * 512 + head * 64 + bj * 32 + fq * 8) = w; }
.LBB0_630:
	v_pk_mul_f32 v[122:123], v[110:111], v[110:111]
	v_pk_mul_f32 v[124:125], v[108:109], v[108:109]
	v_pk_mul_f32 v[126:127], v[106:107], v[106:107]
	v_pk_mul_f32 v[128:129], v[104:105], v[104:105]
	v_pk_mov_b32 v[134:135], v[124:125], v[122:123] op_sel:[1,0]
	v_mov_b32_e32 v125, v123
	v_pk_mov_b32 v[122:123], v[128:129], v[126:127] op_sel:[1,0]
	v_mov_b32_e32 v129, v127
	v_mul_f32_e32 v133, v96, v96
	v_mul_f32_e32 v130, v101, v101
	v_mul_f32_e32 v132, v103, v103
	v_pk_add_f32 v[124:125], v[134:135], v[124:125]
	v_pk_add_f32 v[122:123], v[122:123], v[128:129]
	v_mul_f32_e32 v158, v97, v97
	v_mul_f32_e32 v159, v98, v98
	v_mul_f32_e32 v160, v99, v99
	v_and_b32_e32 v162, 64, v157
	v_pk_fma_f32 v[126:127], v[100:101], v[100:101], v[130:131] op_sel_hi:[1,1,0]
	v_pk_fma_f32 v[130:131], v[102:103], v[102:103], v[132:133] op_sel_hi:[1,1,0]
	v_pk_add_f32 v[124:125], v[124:125], v[124:125] op_sel:[0,1] op_sel_hi:[1,0]
	v_pk_add_f32 v[122:123], v[122:123], v[122:123] op_sel:[0,1] op_sel_hi:[1,0]
	v_xor_b32_e32 v161, 16, v157
	v_add_u32_e32 v132, 64, v162
	v_mov_b32_e32 v127, v159
	v_mov_b32_e32 v131, v160
	v_mov_b32_e32 v125, v133
	v_mov_b32_e32 v123, v158
	v_cmp_lt_i32_e32 vcc, v161, v132
	v_pk_add_f32 v[126:127], v[126:127], v[130:131]
	v_pk_add_f32 v[122:123], v[124:125], v[122:123]
	v_cndmask_b32_e32 v128, v157, v161, vcc
	v_pk_add_f32 v[122:123], v[122:123], v[126:127]
	v_lshlrev_b32_e32 v128, 2, v128
	v_add_f32_e32 v122, v122, v123
	ds_bpermute_b32 v123, v128, v122
	v_xor_b32_e32 v124, 32, v157
	v_cmp_lt_i32_e32 vcc, v124, v132
	s_lshl_b32 s7, s48, 8
	v_lshlrev_b64 v[120:121], 10, v[120:121]
	v_cndmask_b32_e32 v124, v157, v124, vcc
	v_lshlrev_b32_e32 v124, 2, v124
	s_waitcnt lgkmcnt(0)
	v_add_f32_e32 v122, v122, v123
	ds_bpermute_b32 v123, v124, v122
	s_or_b32 s70, s7, s33
	v_lshl_add_u64 v[120:121], s[4:5], 0, v[120:121]
	s_ashr_i32 s71, s70, 31
	v_lshl_add_u64 v[120:121], s[70:71], 1, v[120:121]
	s_waitcnt lgkmcnt(0)
	v_add_f32_e32 v122, v122, v123
	v_fmamk_f32 v122, v122, 0x3c800000, v156
	v_mul_f32_e32 v123, 0x4b800000, v122
	v_cmp_gt_f32_e32 vcc, s13, v122
	s_nop 1
	v_cndmask_b32_e32 v122, v122, v123, vcc
	v_rsq_f32_e32 v124, v122
	v_lshl_add_u64 v[122:123], v[144:145], 1, v[120:121]
	v_mul_f32_e32 v125, 0x45800000, v124
	v_cndmask_b32_e32 v124, v124, v125, vcc
	v_pk_mul_f32 v[104:105], v[104:105], v[124:125] op_sel_hi:[1,0]
	v_pk_mul_f32 v[106:107], v[106:107], v[124:125] op_sel_hi:[1,0]
	v_pk_mul_f32 v[108:109], v[108:109], v[124:125] op_sel_hi:[1,0]
	v_pk_mul_f32 v[110:111], v[110:111], v[124:125] op_sel_hi:[1,0]
	v_pk_mul_f32 v[100:101], v[100:101], v[124:125] op_sel_hi:[1,0]
	v_pk_mul_f32 v[102:103], v[102:103], v[124:125] op_sel_hi:[1,0]
	v_pk_mul_f32 v[96:97], v[96:97], v[124:125] op_sel_hi:[1,0]
	v_pk_mul_f32 v[98:99], v[98:99], v[124:125] op_sel_hi:[1,0]
	v_pk_mul_f32 v[110:111], v[192:193], v[110:111]
	v_pk_mul_f32 v[114:115], v[196:197], v[106:107]
	v_pk_mul_f32 v[106:107], v[194:195], v[104:105]
	v_pk_mul_f32 v[108:109], v[190:191], v[108:109]
	v_cvt_pk_bf16_f32 v105, v110, v111
	v_cvt_pk_bf16_f32 v106, v106, v107
	v_cvt_pk_bf16_f32 v107, v114, v115
	v_lshl_add_u64 v[116:117], v[120:121], 0, 64
	v_cvt_pk_bf16_f32 v104, v108, v109
	global_store_dwordx4 v[122:123], v[104:107], off
	s_nop 0
	v_pk_mul_f32 v[102:103], v[200:201], v[102:103]
	v_pk_mul_f32 v[100:101], v[198:199], v[100:101]
	v_pk_mul_f32 v[98:99], v[204:205], v[98:99]
	v_pk_mul_f32 v[96:97], v[202:203], v[96:97]
	v_cvt_pk_bf16_f32 v112, v100, v101
	v_cvt_pk_bf16_f32 v113, v102, v103
	v_cvt_pk_bf16_f32 v115, v98, v99
	s_nop 0
	v_cvt_pk_bf16_f32 v114, v96, v97

; __device__ __forceinline__ unsigned cvt_pk_bf16(float lo, float hi) { unsigned r; asm("v_cvt_pk_bf16_f32 %0, %1, %2" : "=v"(r) : "v"(lo), "v"(hi)); return r; }
;     __device__ __forceinline__ void epi(Acc& acc, const Unit& u, int wr, int wc, int fr, int fq) const {
;     ...
;                     const int head = u.pn * 4 + wc; float s = 0.f;
; #pragma unroll
;                     for (int bj = 0; bj < 2; ++bj)
; #pragma unroll
;                         for (int n = 0; n < 2; ++n) { const f32x4 x = acc[ai][bj][m][n]; s += (x[0] * x[0] + x[1] * x[1]) + (x[2] * x[2] + x[3] * x[3]); }
;                     s += __shfl_xor(s, 16); s += __shfl_xor(s, 32);
;                     const float r2 = rsqrtf(s * (1.f / 64.f) + EPS);
; #pragma unroll
;                     for (int bj = 0; bj < 2; ++bj) { const f32x4 g0 = *(const f32x4*)(kng + bj * 32 + fq * 8), g1 = *(const f32x4*)(kng + bj * 32 + fq * 8 + 4);
;                         const f32x4 a = acc[ai][bj][m][0] * r2 * g0, b = acc[ai][bj][m][1] * r2 * g1;
;                         u32x4 w; w.x = cvt_pk_bf16(a[0], a[1]); w.y = cvt_pk_bf16(a[2], a[3]); w.z = cvt_pk_bf16(b[0], b[1]); w.w = cvt_pk_bf16(b[2], b[3]);
;                         *(u32x4*)(KN + row * 512 + head * 64 + bj * 32 + fq * 8) = w; }
.LBB0_633:
	v_pk_mul_f32 v[106:107], v[94:95], v[94:95]
	v_pk_mul_f32 v[108:109], v[92:93], v[92:93]
	v_pk_mul_f32 v[110:111], v[90:91], v[90:91]
	v_pk_mul_f32 v[112:113], v[88:89], v[88:89]
	v_pk_mov_b32 v[118:119], v[108:109], v[106:107] op_sel:[1,0]
	v_mov_b32_e32 v109, v107
	v_pk_mov_b32 v[106:107], v[112:113], v[110:111] op_sel:[1,0]
	v_mov_b32_e32 v113, v111
	v_mul_f32_e32 v117, v80, v80
	v_mul_f32_e32 v114, v85, v85
	v_mul_f32_e32 v116, v87, v87
	v_pk_add_f32 v[108:109], v[118:119], v[108:109]
	v_pk_add_f32 v[106:107], v[106:107], v[112:113]
	v_mul_f32_e32 v120, v81, v81
	v_mul_f32_e32 v121, v82, v82
	v_mul_f32_e32 v122, v83, v83
	v_and_b32_e32 v124, 64, v157
	v_pk_fma_f32 v[110:111], v[84:85], v[84:85], v[114:115] op_sel_hi:[1,1,0]
	v_pk_fma_f32 v[114:115], v[86:87], v[86:87], v[116:117] op_sel_hi:[1,1,0]
	v_pk_add_f32 v[108:109], v[108:109], v[108:109] op_sel:[0,1] op_sel_hi:[1,0]
	v_pk_add_f32 v[106:107], v[106:107], v[106:107] op_sel:[0,1] op_sel_hi:[1,0]
	v_xor_b32_e32 v123, 16, v157
	v_add_u32_e32 v116, 64, v124
	v_mov_b32_e32 v111, v121
	v_mov_b32_e32 v115, v122
	v_mov_b32_e32 v109, v117
	v_mov_b32_e32 v107, v120
	v_cmp_lt_i32_e32 vcc, v123, v116
	v_pk_add_f32 v[110:111], v[110:111], v[114:115]
	v_pk_add_f32 v[106:107], v[108:109], v[106:107]
	v_cndmask_b32_e32 v112, v157, v123, vcc
	v_pk_add_f32 v[106:107], v[106:107], v[110:111]
	v_lshlrev_b32_e32 v112, 2, v112
	v_add_f32_e32 v106, v106, v107
	ds_bpermute_b32 v107, v112, v106
	v_xor_b32_e32 v108, 32, v157
	v_cmp_lt_i32_e32 vcc, v108, v116
	s_lshl_b32 s7, s48, 8
	v_lshlrev_b64 v[104:105], 10, v[104:105]
	v_cndmask_b32_e32 v108, v157, v108, vcc
	v_lshlrev_b32_e32 v108, 2, v108
	s_waitcnt lgkmcnt(0)
	v_add_f32_e32 v106, v106, v107
	ds_bpermute_b32 v107, v108, v106
	s_or_b32 s70, s7, s33
	v_lshl_add_u64 v[104:105], s[4:5], 0, v[104:105]
	s_ashr_i32 s71, s70, 31
	v_lshl_add_u64 v[104:105], s[70:71], 1, v[104:105]
	s_waitcnt lgkmcnt(0)
	v_add_f32_e32 v106, v106, v107
	v_fmamk_f32 v106, v106, 0x3c800000, v156
	v_mul_f32_e32 v107, 0x4b800000, v106
	v_cmp_gt_f32_e32 vcc, s13, v106
	s_nop 1
	v_cndmask_b32_e32 v106, v106, v107, vcc
	v_rsq_f32_e32 v108, v106
	v_lshl_add_u64 v[106:107], v[144:145], 1, v[104:105]
	v_mul_f32_e32 v109, 0x45800000, v108
	v_cndmask_b32_e32 v108, v108, v109, vcc
	v_pk_mul_f32 v[88:89], v[88:89], v[108:109] op_sel_hi:[1,0]
	v_pk_mul_f32 v[90:91], v[90:91], v[108:109] op_sel_hi:[1,0]
	v_pk_mul_f32 v[92:93], v[92:93], v[108:109] op_sel_hi:[1,0]
	v_pk_mul_f32 v[94:95], v[94:95], v[108:109] op_sel_hi:[1,0]
	v_pk_mul_f32 v[84:85], v[84:85], v[108:109] op_sel_hi:[1,0]
	v_pk_mul_f32 v[86:87], v[86:87], v[108:109] op_sel_hi:[1,0]
	v_pk_mul_f32 v[80:81], v[80:81], v[108:109] op_sel_hi:[1,0]
	v_pk_mul_f32 v[82:83], v[82:83], v[108:109] op_sel_hi:[1,0]
	v_pk_mul_f32 v[94:95], v[192:193], v[94:95]
	v_pk_mul_f32 v[98:99], v[196:197], v[90:91]
	v_pk_mul_f32 v[90:91], v[194:195], v[88:89]
	v_pk_mul_f32 v[92:93], v[190:191], v[92:93]
	v_cvt_pk_bf16_f32 v89, v94, v95
	v_cvt_pk_bf16_f32 v90, v90, v91
	v_cvt_pk_bf16_f32 v91, v98, v99
	v_lshl_add_u64 v[100:101], v[104:105], 0, 64
	v_cvt_pk_bf16_f32 v88, v92, v93
	global_store_dwordx4 v[106:107], v[88:91], off
	s_nop 0
	v_pk_mul_f32 v[86:87], v[200:201], v[86:87]
	v_pk_mul_f32 v[84:85], v[198:199], v[84:85]
	v_pk_mul_f32 v[82:83], v[204:205], v[82:83]
	v_pk_mul_f32 v[80:81], v[202:203], v[80:81]
	v_cvt_pk_bf16_f32 v96, v84, v85
	v_cvt_pk_bf16_f32 v97, v86, v87
	v_cvt_pk_bf16_f32 v99, v82, v83
	s_nop 0
	v_cvt_pk_bf16_f32 v98, v80, v81

; __device__ __forceinline__ unsigned cvt_pk_bf16(float lo, float hi) { unsigned r; asm("v_cvt_pk_bf16_f32 %0, %1, %2" : "=v"(r) : "v"(lo), "v"(hi)); return r; }
;     __device__ __forceinline__ void epi(Acc& acc, const Unit& u, int wr, int wc, int fr, int fq) const {
;     ...
;                     const int head = u.pn * 4 + wc; float s = 0.f;
; #pragma unroll
;                     for (int bj = 0; bj < 2; ++bj)
; #pragma unroll
;                         for (int n = 0; n < 2; ++n) { const f32x4 x = acc[ai][bj][m][n]; s += (x[0] * x[0] + x[1] * x[1]) + (x[2] * x[2] + x[3] * x[3]); }
;                     s += __shfl_xor(s, 16); s += __shfl_xor(s, 32);
;                     const float r2 = rsqrtf(s * (1.f / 64.f) + EPS);
; #pragma unroll
;                     for (int bj = 0; bj < 2; ++bj) { const f32x4 g0 = *(const f32x4*)(kng + bj * 32 + fq * 8), g1 = *(const f32x4*)(kng + bj * 32 + fq * 8 + 4);
;                         const f32x4 a = acc[ai][bj][m][0] * r2 * g0, b = acc[ai][bj][m][1] * r2 * g1;
;                         u32x4 w; w.x = cvt_pk_bf16(a[0], a[1]); w.y = cvt_pk_bf16(a[2], a[3]); w.z = cvt_pk_bf16(b[0], b[1]); w.w = cvt_pk_bf16(b[2], b[3]);
;                         *(u32x4*)(KN + row * 512 + head * 64 + bj * 32 + fq * 8) = w; }
.LBB0_636:
	v_pk_mul_f32 v[90:91], v[78:79], v[78:79]
	v_pk_mul_f32 v[92:93], v[76:77], v[76:77]
	v_pk_mul_f32 v[94:95], v[74:75], v[74:75]
	v_pk_mul_f32 v[96:97], v[72:73], v[72:73]
	v_pk_mov_b32 v[102:103], v[92:93], v[90:91] op_sel:[1,0]
	v_mov_b32_e32 v93, v91
	v_pk_mov_b32 v[90:91], v[96:97], v[94:95] op_sel:[1,0]
	v_mov_b32_e32 v97, v95
	v_mul_f32_e32 v101, v64, v64
	v_mul_f32_e32 v98, v69, v69
	v_mul_f32_e32 v100, v71, v71
	v_pk_add_f32 v[92:93], v[102:103], v[92:93]
	v_pk_add_f32 v[90:91], v[90:91], v[96:97]
	v_mul_f32_e32 v104, v65, v65
	v_mul_f32_e32 v105, v66, v66
	v_mul_f32_e32 v106, v67, v67
	v_and_b32_e32 v108, 64, v157
	v_pk_fma_f32 v[94:95], v[68:69], v[68:69], v[98:99] op_sel_hi:[1,1,0]
	v_pk_fma_f32 v[98:99], v[70:71], v[70:71], v[100:101] op_sel_hi:[1,1,0]
	v_pk_add_f32 v[92:93], v[92:93], v[92:93] op_sel:[0,1] op_sel_hi:[1,0]
	v_pk_add_f32 v[90:91], v[90:91], v[90:91] op_sel:[0,1] op_sel_hi:[1,0]
	v_xor_b32_e32 v107, 16, v157
	v_add_u32_e32 v100, 64, v108
	v_mov_b32_e32 v95, v105
	v_mov_b32_e32 v99, v106
	v_mov_b32_e32 v93, v101
	v_mov_b32_e32 v91, v104
	v_cmp_lt_i32_e32 vcc, v107, v100
	v_pk_add_f32 v[94:95], v[94:95], v[98:99]
	v_pk_add_f32 v[90:91], v[92:93], v[90:91]
	v_cndmask_b32_e32 v96, v157, v107, vcc
	v_pk_add_f32 v[90:91], v[90:91], v[94:95]
	v_lshlrev_b32_e32 v96, 2, v96
	v_add_f32_e32 v90, v90, v91
	ds_bpermute_b32 v91, v96, v90
	v_xor_b32_e32 v92, 32, v157
	v_cmp_lt_i32_e32 vcc, v92, v100
	s_lshl_b32 s7, s48, 8
	v_lshlrev_b64 v[88:89], 10, v[88:89]
	v_cndmask_b32_e32 v92, v157, v92, vcc
	v_lshlrev_b32_e32 v92, 2, v92
	s_waitcnt lgkmcnt(0)
	v_add_f32_e32 v90, v90, v91
	ds_bpermute_b32 v91, v92, v90
	s_or_b32 s70, s7, s33
	v_lshl_add_u64 v[88:89], s[4:5], 0, v[88:89]
	s_ashr_i32 s71, s70, 31
	v_lshl_add_u64 v[88:89], s[70:71], 1, v[88:89]
	s_waitcnt lgkmcnt(0)
	v_add_f32_e32 v90, v90, v91
	v_fmamk_f32 v90, v90, 0x3c800000, v156
	v_mul_f32_e32 v91, 0x4b800000, v90
	v_cmp_gt_f32_e32 vcc, s13, v90
	s_nop 1
	v_cndmask_b32_e32 v90, v90, v91, vcc
	v_rsq_f32_e32 v92, v90
	v_lshl_add_u64 v[90:91], v[144:145], 1, v[88:89]
	v_mul_f32_e32 v93, 0x45800000, v92
	v_cndmask_b32_e32 v92, v92, v93, vcc
	v_pk_mul_f32 v[72:73], v[72:73], v[92:93] op_sel_hi:[1,0]
	v_pk_mul_f32 v[74:75], v[74:75], v[92:93] op_sel_hi:[1,0]
	v_pk_mul_f32 v[76:77], v[76:77], v[92:93] op_sel_hi:[1,0]
	v_pk_mul_f32 v[78:79], v[78:79], v[92:93] op_sel_hi:[1,0]
	v_pk_mul_f32 v[68:69], v[68:69], v[92:93] op_sel_hi:[1,0]
	v_pk_mul_f32 v[70:71], v[70:71], v[92:93] op_sel_hi:[1,0]
	v_pk_mul_f32 v[64:65], v[64:65], v[92:93] op_sel_hi:[1,0]
	v_pk_mul_f32 v[66:67], v[66:67], v[92:93] op_sel_hi:[1,0]
	v_pk_mul_f32 v[78:79], v[192:193], v[78:79]
	v_pk_mul_f32 v[82:83], v[196:197], v[74:75]
	v_pk_mul_f32 v[74:75], v[194:195], v[72:73]
	v_pk_mul_f32 v[76:77], v[190:191], v[76:77]
	v_cvt_pk_bf16_f32 v73, v78, v79
	v_cvt_pk_bf16_f32 v74, v74, v75
	v_cvt_pk_bf16_f32 v75, v82, v83
	v_lshl_add_u64 v[84:85], v[88:89], 0, 64
	v_cvt_pk_bf16_f32 v72, v76, v77
	global_store_dwordx4 v[90:91], v[72:75], off
	s_nop 0
	v_pk_mul_f32 v[70:71], v[200:201], v[70:71]
	v_pk_mul_f32 v[68:69], v[198:199], v[68:69]
	v_pk_mul_f32 v[66:67], v[204:205], v[66:67]
	v_pk_mul_f32 v[64:65], v[202:203], v[64:65]
	v_cvt_pk_bf16_f32 v80, v68, v69
	v_cvt_pk_bf16_f32 v81, v70, v71
	v_cvt_pk_bf16_f32 v83, v66, v67
	s_nop 0
	v_cvt_pk_bf16_f32 v82, v64, v65

; __device__ __forceinline__ unsigned cvt_pk_bf16(float lo, float hi) { unsigned r; asm("v_cvt_pk_bf16_f32 %0, %1, %2" : "=v"(r) : "v"(lo), "v"(hi)); return r; }
;     __device__ __forceinline__ void epi(Acc& acc, const Unit& u, int wr, int wc, int fr, int fq) const {
;     ...
;                     const int head = u.pn * 4 + wc; float s = 0.f;
; #pragma unroll
;                     for (int bj = 0; bj < 2; ++bj)
; #pragma unroll
;                         for (int n = 0; n < 2; ++n) { const f32x4 x = acc[ai][bj][m][n]; s += (x[0] * x[0] + x[1] * x[1]) + (x[2] * x[2] + x[3] * x[3]); }
;                     s += __shfl_xor(s, 16); s += __shfl_xor(s, 32);
;                     const float r2 = rsqrtf(s * (1.f / 64.f) + EPS);
; #pragma unroll
;                     for (int bj = 0; bj < 2; ++bj) { const f32x4 g0 = *(const f32x4*)(kng + bj * 32 + fq * 8), g1 = *(const f32x4*)(kng + bj * 32 + fq * 8 + 4);
;                         const f32x4 a = acc[ai][bj][m][0] * r2 * g0, b = acc[ai][bj][m][1] * r2 * g1;
;                         u32x4 w; w.x = cvt_pk_bf16(a[0], a[1]); w.y = cvt_pk_bf16(a[2], a[3]); w.z = cvt_pk_bf16(b[0], b[1]); w.w = cvt_pk_bf16(b[2], b[3]);
;                         *(u32x4*)(KN + row * 512 + head * 64 + bj * 32 + fq * 8) = w; }
.LBB0_639:
	v_pk_mul_f32 v[74:75], v[62:63], v[62:63]
	v_pk_mul_f32 v[76:77], v[60:61], v[60:61]
	v_pk_mul_f32 v[78:79], v[58:59], v[58:59]
	v_pk_mul_f32 v[80:81], v[56:57], v[56:57]
	v_pk_mov_b32 v[86:87], v[76:77], v[74:75] op_sel:[1,0]
	v_mov_b32_e32 v77, v75
	v_pk_mov_b32 v[74:75], v[80:81], v[78:79] op_sel:[1,0]
	v_mov_b32_e32 v81, v79
	v_mul_f32_e32 v85, v48, v48
	v_mul_f32_e32 v82, v53, v53
	v_mul_f32_e32 v84, v55, v55
	v_pk_add_f32 v[76:77], v[86:87], v[76:77]
	v_pk_add_f32 v[74:75], v[74:75], v[80:81]
	v_mul_f32_e32 v88, v49, v49
	v_mul_f32_e32 v89, v50, v50
	v_mul_f32_e32 v90, v51, v51
	v_and_b32_e32 v92, 64, v157
	v_pk_fma_f32 v[78:79], v[52:53], v[52:53], v[82:83] op_sel_hi:[1,1,0]
	v_pk_fma_f32 v[82:83], v[54:55], v[54:55], v[84:85] op_sel_hi:[1,1,0]
	v_pk_add_f32 v[76:77], v[76:77], v[76:77] op_sel:[0,1] op_sel_hi:[1,0]
	v_pk_add_f32 v[74:75], v[74:75], v[74:75] op_sel:[0,1] op_sel_hi:[1,0]
	v_xor_b32_e32 v91, 16, v157
	v_add_u32_e32 v84, 64, v92
	v_mov_b32_e32 v79, v89
	v_mov_b32_e32 v83, v90
	v_mov_b32_e32 v77, v85
	v_mov_b32_e32 v75, v88
	v_cmp_lt_i32_e32 vcc, v91, v84
	v_pk_add_f32 v[78:79], v[78:79], v[82:83]
	v_pk_add_f32 v[74:75], v[76:77], v[74:75]
	v_cndmask_b32_e32 v80, v157, v91, vcc
	v_pk_add_f32 v[74:75], v[74:75], v[78:79]
	v_lshlrev_b32_e32 v80, 2, v80
	v_add_f32_e32 v74, v74, v75
	ds_bpermute_b32 v75, v80, v74
	v_xor_b32_e32 v76, 32, v157
	v_cmp_lt_i32_e32 vcc, v76, v84
	s_lshl_b32 s7, s48, 8
	v_lshlrev_b64 v[72:73], 10, v[72:73]
	v_cndmask_b32_e32 v76, v157, v76, vcc
	v_lshlrev_b32_e32 v76, 2, v76
	s_waitcnt lgkmcnt(0)
	v_add_f32_e32 v74, v74, v75
	ds_bpermute_b32 v75, v76, v74
	s_or_b32 s70, s7, s33
	v_lshl_add_u64 v[72:73], s[4:5], 0, v[72:73]
	s_ashr_i32 s71, s70, 31
	v_lshl_add_u64 v[72:73], s[70:71], 1, v[72:73]
	s_waitcnt lgkmcnt(0)
	v_add_f32_e32 v74, v74, v75
	v_fmamk_f32 v74, v74, 0x3c800000, v156
	v_mul_f32_e32 v75, 0x4b800000, v74
	v_cmp_gt_f32_e32 vcc, s13, v74
	s_nop 1
	v_cndmask_b32_e32 v74, v74, v75, vcc
	v_rsq_f32_e32 v76, v74
	v_lshl_add_u64 v[74:75], v[144:145], 1, v[72:73]
	v_mul_f32_e32 v77, 0x45800000, v76
	v_cndmask_b32_e32 v76, v76, v77, vcc
	v_pk_mul_f32 v[56:57], v[56:57], v[76:77] op_sel_hi:[1,0]
	v_pk_mul_f32 v[58:59], v[58:59], v[76:77] op_sel_hi:[1,0]
	v_pk_mul_f32 v[60:61], v[60:61], v[76:77] op_sel_hi:[1,0]
	v_pk_mul_f32 v[62:63], v[62:63], v[76:77] op_sel_hi:[1,0]
	v_pk_mul_f32 v[52:53], v[52:53], v[76:77] op_sel_hi:[1,0]
	v_pk_mul_f32 v[54:55], v[54:55], v[76:77] op_sel_hi:[1,0]
	v_pk_mul_f32 v[48:49], v[48:49], v[76:77] op_sel_hi:[1,0]
	v_pk_mul_f32 v[50:51], v[50:51], v[76:77] op_sel_hi:[1,0]
	v_pk_mul_f32 v[62:63], v[192:193], v[62:63]
	v_pk_mul_f32 v[66:67], v[196:197], v[58:59]
	v_pk_mul_f32 v[58:59], v[194:195], v[56:57]
	v_pk_mul_f32 v[60:61], v[190:191], v[60:61]
	v_cvt_pk_bf16_f32 v57, v62, v63
	v_cvt_pk_bf16_f32 v58, v58, v59
	v_cvt_pk_bf16_f32 v59, v66, v67
	v_lshl_add_u64 v[68:69], v[72:73], 0, 64
	v_cvt_pk_bf16_f32 v56, v60, v61
	global_store_dwordx4 v[74:75], v[56:59], off
	s_nop 0
	v_pk_mul_f32 v[54:55], v[200:201], v[54:55]
	v_pk_mul_f32 v[52:53], v[198:199], v[52:53]
	v_pk_mul_f32 v[50:51], v[204:205], v[50:51]
	v_pk_mul_f32 v[48:49], v[202:203], v[48:49]
	v_cvt_pk_bf16_f32 v64, v52, v53
	v_cvt_pk_bf16_f32 v65, v54, v55
	v_cvt_pk_bf16_f32 v67, v50, v51
	s_nop 0
	v_cvt_pk_bf16_f32 v66, v48, v49

; __device__ __forceinline__ unsigned cvt_pk_bf16(float lo, float hi) { unsigned r; asm("v_cvt_pk_bf16_f32 %0, %1, %2" : "=v"(r) : "v"(lo), "v"(hi)); return r; }
;     __device__ __forceinline__ void epi(Acc& acc, const Unit& u, int wr, int wc, int fr, int fq) const {
;     ...
;                     const int head = u.pn * 4 + wc; float s = 0.f;
; #pragma unroll
;                     for (int bj = 0; bj < 2; ++bj)
; #pragma unroll
;                         for (int n = 0; n < 2; ++n) { const f32x4 x = acc[ai][bj][m][n]; s += (x[0] * x[0] + x[1] * x[1]) + (x[2] * x[2] + x[3] * x[3]); }
;                     s += __shfl_xor(s, 16); s += __shfl_xor(s, 32);
;                     const float r2 = rsqrtf(s * (1.f / 64.f) + EPS);
; #pragma unroll
;                     for (int bj = 0; bj < 2; ++bj) { const f32x4 g0 = *(const f32x4*)(kng + bj * 32 + fq * 8), g1 = *(const f32x4*)(kng + bj * 32 + fq * 8 + 4);
;                         const f32x4 a = acc[ai][bj][m][0] * r2 * g0, b = acc[ai][bj][m][1] * r2 * g1;
;                         u32x4 w; w.x = cvt_pk_bf16(a[0], a[1]); w.y = cvt_pk_bf16(a[2], a[3]); w.z = cvt_pk_bf16(b[0], b[1]); w.w = cvt_pk_bf16(b[2], b[3]);
;                         *(u32x4*)(KN + row * 512 + head * 64 + bj * 32 + fq * 8) = w; }
.LBB0_642:
	v_pk_mul_f32 v[58:59], v[46:47], v[46:47]
	v_pk_mul_f32 v[60:61], v[44:45], v[44:45]
	v_pk_mul_f32 v[62:63], v[42:43], v[42:43]
	v_pk_mul_f32 v[64:65], v[40:41], v[40:41]
	v_pk_mov_b32 v[70:71], v[60:61], v[58:59] op_sel:[1,0]
	v_mov_b32_e32 v61, v59
	v_pk_mov_b32 v[58:59], v[64:65], v[62:63] op_sel:[1,0]
	v_mov_b32_e32 v65, v63
	v_mul_f32_e32 v69, v32, v32
	v_mul_f32_e32 v66, v37, v37
	v_mul_f32_e32 v68, v39, v39
	v_pk_add_f32 v[60:61], v[70:71], v[60:61]
	v_pk_add_f32 v[58:59], v[58:59], v[64:65]
	v_mul_f32_e32 v72, v33, v33
	v_mul_f32_e32 v73, v34, v34
	v_mul_f32_e32 v74, v35, v35
	v_and_b32_e32 v76, 64, v157
	v_pk_fma_f32 v[62:63], v[36:37], v[36:37], v[66:67] op_sel_hi:[1,1,0]
	v_pk_fma_f32 v[66:67], v[38:39], v[38:39], v[68:69] op_sel_hi:[1,1,0]
	v_pk_add_f32 v[60:61], v[60:61], v[60:61] op_sel:[0,1] op_sel_hi:[1,0]
	v_pk_add_f32 v[58:59], v[58:59], v[58:59] op_sel:[0,1] op_sel_hi:[1,0]
	v_xor_b32_e32 v75, 16, v157
	v_add_u32_e32 v68, 64, v76
	v_mov_b32_e32 v63, v73
	v_mov_b32_e32 v67, v74
	v_mov_b32_e32 v61, v69
	v_mov_b32_e32 v59, v72
	v_cmp_lt_i32_e32 vcc, v75, v68
	v_pk_add_f32 v[62:63], v[62:63], v[66:67]
	v_pk_add_f32 v[58:59], v[60:61], v[58:59]
	v_cndmask_b32_e32 v64, v157, v75, vcc
	v_pk_add_f32 v[58:59], v[58:59], v[62:63]
	v_lshlrev_b32_e32 v64, 2, v64
	v_add_f32_e32 v58, v58, v59
	ds_bpermute_b32 v59, v64, v58
	v_xor_b32_e32 v60, 32, v157
	v_cmp_lt_i32_e32 vcc, v60, v68
	s_lshl_b32 s7, s48, 8
	v_lshlrev_b64 v[56:57], 10, v[56:57]
	v_cndmask_b32_e32 v60, v157, v60, vcc
	v_lshlrev_b32_e32 v60, 2, v60
	s_waitcnt lgkmcnt(0)
	v_add_f32_e32 v58, v58, v59
	ds_bpermute_b32 v59, v60, v58
	s_or_b32 s70, s7, s33
	v_lshl_add_u64 v[56:57], s[4:5], 0, v[56:57]
	s_ashr_i32 s71, s70, 31
	v_lshl_add_u64 v[56:57], s[70:71], 1, v[56:57]
	s_waitcnt lgkmcnt(0)
	v_add_f32_e32 v58, v58, v59
	v_fmamk_f32 v58, v58, 0x3c800000, v156
	v_mul_f32_e32 v59, 0x4b800000, v58
	v_cmp_gt_f32_e32 vcc, s13, v58
	s_nop 1
	v_cndmask_b32_e32 v58, v58, v59, vcc
	v_rsq_f32_e32 v60, v58
	v_lshl_add_u64 v[58:59], v[144:145], 1, v[56:57]
	v_mul_f32_e32 v61, 0x45800000, v60
	v_cndmask_b32_e32 v60, v60, v61, vcc
	v_pk_mul_f32 v[40:41], v[40:41], v[60:61] op_sel_hi:[1,0]
	v_pk_mul_f32 v[42:43], v[42:43], v[60:61] op_sel_hi:[1,0]
	v_pk_mul_f32 v[44:45], v[44:45], v[60:61] op_sel_hi:[1,0]
	v_pk_mul_f32 v[46:47], v[46:47], v[60:61] op_sel_hi:[1,0]
	v_pk_mul_f32 v[36:37], v[36:37], v[60:61] op_sel_hi:[1,0]
	v_pk_mul_f32 v[38:39], v[38:39], v[60:61] op_sel_hi:[1,0]
	v_pk_mul_f32 v[32:33], v[32:33], v[60:61] op_sel_hi:[1,0]
	v_pk_mul_f32 v[34:35], v[34:35], v[60:61] op_sel_hi:[1,0]
	v_pk_mul_f32 v[46:47], v[192:193], v[46:47]
	v_pk_mul_f32 v[50:51], v[196:197], v[42:43]
	v_pk_mul_f32 v[42:43], v[194:195], v[40:41]
	v_pk_mul_f32 v[44:45], v[190:191], v[44:45]
	v_cvt_pk_bf16_f32 v41, v46, v47
	v_cvt_pk_bf16_f32 v42, v42, v43
	v_cvt_pk_bf16_f32 v43, v50, v51
	v_lshl_add_u64 v[52:53], v[56:57], 0, 64
	v_cvt_pk_bf16_f32 v40, v44, v45
	global_store_dwordx4 v[58:59], v[40:43], off
	s_nop 0
	v_pk_mul_f32 v[38:39], v[200:201], v[38:39]
	v_pk_mul_f32 v[36:37], v[198:199], v[36:37]
	v_pk_mul_f32 v[34:35], v[204:205], v[34:35]
	v_pk_mul_f32 v[32:33], v[202:203], v[32:33]
	v_cvt_pk_bf16_f32 v48, v36, v37
	v_cvt_pk_bf16_f32 v49, v38, v39
	v_cvt_pk_bf16_f32 v51, v34, v35
	s_nop 0
	v_cvt_pk_bf16_f32 v50, v32, v33

; __device__ __forceinline__ unsigned cvt_pk_bf16(float lo, float hi) { unsigned r; asm("v_cvt_pk_bf16_f32 %0, %1, %2" : "=v"(r) : "v"(lo), "v"(hi)); return r; }
;     __device__ __forceinline__ void epi(Acc& acc, const Unit& u, int wr, int wc, int fr, int fq) const {
;     ...
;                     const int head = u.pn * 4 + wc; float s = 0.f;
; #pragma unroll
;                     for (int bj = 0; bj < 2; ++bj)
; #pragma unroll
;                         for (int n = 0; n < 2; ++n) { const f32x4 x = acc[ai][bj][m][n]; s += (x[0] * x[0] + x[1] * x[1]) + (x[2] * x[2] + x[3] * x[3]); }
;                     s += __shfl_xor(s, 16); s += __shfl_xor(s, 32);
;                     const float r2 = rsqrtf(s * (1.f / 64.f) + EPS);
; #pragma unroll
;                     for (int bj = 0; bj < 2; ++bj) { const f32x4 g0 = *(const f32x4*)(kng + bj * 32 + fq * 8), g1 = *(const f32x4*)(kng + bj * 32 + fq * 8 + 4);
;                         const f32x4 a = acc[ai][bj][m][0] * r2 * g0, b = acc[ai][bj][m][1] * r2 * g1;
;                         u32x4 w; w.x = cvt_pk_bf16(a[0], a[1]); w.y = cvt_pk_bf16(a[2], a[3]); w.z = cvt_pk_bf16(b[0], b[1]); w.w = cvt_pk_bf16(b[2], b[3]);
;                         *(u32x4*)(KN + row * 512 + head * 64 + bj * 32 + fq * 8) = w; }
.LBB0_645:
	v_pk_mul_f32 v[42:43], v[30:31], v[30:31]
	v_pk_mul_f32 v[44:45], v[28:29], v[28:29]
	v_pk_mul_f32 v[46:47], v[26:27], v[26:27]
	v_pk_mul_f32 v[48:49], v[24:25], v[24:25]
	v_pk_mov_b32 v[54:55], v[44:45], v[42:43] op_sel:[1,0]
	v_mov_b32_e32 v45, v43
	v_pk_mov_b32 v[42:43], v[48:49], v[46:47] op_sel:[1,0]
	v_mov_b32_e32 v49, v47
	v_mul_f32_e32 v53, v16, v16
	v_mul_f32_e32 v50, v21, v21
	v_mul_f32_e32 v52, v23, v23
	v_pk_add_f32 v[44:45], v[54:55], v[44:45]
	v_pk_add_f32 v[42:43], v[42:43], v[48:49]
	v_mul_f32_e32 v56, v17, v17
	v_mul_f32_e32 v57, v18, v18
	v_mul_f32_e32 v58, v19, v19
	v_and_b32_e32 v60, 64, v157
	v_pk_fma_f32 v[46:47], v[20:21], v[20:21], v[50:51] op_sel_hi:[1,1,0]
	v_pk_fma_f32 v[50:51], v[22:23], v[22:23], v[52:53] op_sel_hi:[1,1,0]
	v_pk_add_f32 v[44:45], v[44:45], v[44:45] op_sel:[0,1] op_sel_hi:[1,0]
	v_pk_add_f32 v[42:43], v[42:43], v[42:43] op_sel:[0,1] op_sel_hi:[1,0]
	v_xor_b32_e32 v59, 16, v157
	v_add_u32_e32 v52, 64, v60
	v_mov_b32_e32 v47, v57
	v_mov_b32_e32 v51, v58
	v_mov_b32_e32 v45, v53
	v_mov_b32_e32 v43, v56
	v_cmp_lt_i32_e32 vcc, v59, v52
	v_pk_add_f32 v[46:47], v[46:47], v[50:51]
	v_pk_add_f32 v[42:43], v[44:45], v[42:43]
	v_cndmask_b32_e32 v48, v157, v59, vcc
	v_pk_add_f32 v[42:43], v[42:43], v[46:47]
	v_lshlrev_b32_e32 v48, 2, v48
	v_add_f32_e32 v42, v42, v43
	ds_bpermute_b32 v43, v48, v42
	v_xor_b32_e32 v44, 32, v157
	v_cmp_lt_i32_e32 vcc, v44, v52
	s_lshl_b32 s7, s48, 8
	v_lshlrev_b64 v[40:41], 10, v[40:41]
	v_cndmask_b32_e32 v44, v157, v44, vcc
	v_lshlrev_b32_e32 v44, 2, v44
	s_waitcnt lgkmcnt(0)
	v_add_f32_e32 v42, v42, v43
	ds_bpermute_b32 v43, v44, v42
	s_or_b32 s70, s7, s33
	v_lshl_add_u64 v[40:41], s[4:5], 0, v[40:41]
	s_ashr_i32 s71, s70, 31
	v_lshl_add_u64 v[40:41], s[70:71], 1, v[40:41]
	s_waitcnt lgkmcnt(0)
	v_add_f32_e32 v42, v42, v43
	v_fmamk_f32 v42, v42, 0x3c800000, v156
	v_mul_f32_e32 v43, 0x4b800000, v42
	v_cmp_gt_f32_e32 vcc, s13, v42
	s_nop 1
	v_cndmask_b32_e32 v42, v42, v43, vcc
	v_rsq_f32_e32 v44, v42
	v_lshl_add_u64 v[42:43], v[144:145], 1, v[40:41]
	v_mul_f32_e32 v45, 0x45800000, v44
	v_cndmask_b32_e32 v44, v44, v45, vcc
	v_pk_mul_f32 v[24:25], v[24:25], v[44:45] op_sel_hi:[1,0]
	v_pk_mul_f32 v[26:27], v[26:27], v[44:45] op_sel_hi:[1,0]
	v_pk_mul_f32 v[28:29], v[28:29], v[44:45] op_sel_hi:[1,0]
	v_pk_mul_f32 v[30:31], v[30:31], v[44:45] op_sel_hi:[1,0]
	v_pk_mul_f32 v[20:21], v[20:21], v[44:45] op_sel_hi:[1,0]
	v_pk_mul_f32 v[22:23], v[22:23], v[44:45] op_sel_hi:[1,0]
	v_pk_mul_f32 v[16:17], v[16:17], v[44:45] op_sel_hi:[1,0]
	v_pk_mul_f32 v[18:19], v[18:19], v[44:45] op_sel_hi:[1,0]
	v_pk_mul_f32 v[30:31], v[192:193], v[30:31]
	v_pk_mul_f32 v[34:35], v[196:197], v[26:27]
	v_pk_mul_f32 v[26:27], v[194:195], v[24:25]
	v_pk_mul_f32 v[28:29], v[190:191], v[28:29]
	v_cvt_pk_bf16_f32 v25, v30, v31
	v_cvt_pk_bf16_f32 v26, v26, v27
	v_cvt_pk_bf16_f32 v27, v34, v35
	v_lshl_add_u64 v[36:37], v[40:41], 0, 64
	v_cvt_pk_bf16_f32 v24, v28, v29
	global_store_dwordx4 v[42:43], v[24:27], off
	s_nop 0
	v_pk_mul_f32 v[22:23], v[200:201], v[22:23]
	v_pk_mul_f32 v[20:21], v[198:199], v[20:21]
	v_pk_mul_f32 v[18:19], v[204:205], v[18:19]
	v_pk_mul_f32 v[16:17], v[202:203], v[16:17]
	v_cvt_pk_bf16_f32 v32, v20, v21
	v_cvt_pk_bf16_f32 v33, v22, v23
	v_cvt_pk_bf16_f32 v35, v18, v19
	s_nop 0
	v_cvt_pk_bf16_f32 v34, v16, v17

; __device__ __forceinline__ unsigned cvt_pk_bf16(float lo, float hi) { unsigned r; asm("v_cvt_pk_bf16_f32 %0, %1, %2" : "=v"(r) : "v"(lo), "v"(hi)); return r; }
;     __device__ __forceinline__ void epi(Acc& acc, const Unit& u, int wr, int wc, int fr, int fq) const {
;     ...
;                     const int head = u.pn * 4 + wc; float s = 0.f;
; #pragma unroll
;                     for (int bj = 0; bj < 2; ++bj)
; #pragma unroll
;                         for (int n = 0; n < 2; ++n) { const f32x4 x = acc[ai][bj][m][n]; s += (x[0] * x[0] + x[1] * x[1]) + (x[2] * x[2] + x[3] * x[3]); }
;                     s += __shfl_xor(s, 16); s += __shfl_xor(s, 32);
;                     const float r2 = rsqrtf(s * (1.f / 64.f) + EPS);
; #pragma unroll
;                     for (int bj = 0; bj < 2; ++bj) { const f32x4 g0 = *(const f32x4*)(kng + bj * 32 + fq * 8), g1 = *(const f32x4*)(kng + bj * 32 + fq * 8 + 4);
;                         const f32x4 a = acc[ai][bj][m][0] * r2 * g0, b = acc[ai][bj][m][1] * r2 * g1;
;                         u32x4 w; w.x = cvt_pk_bf16(a[0], a[1]); w.y = cvt_pk_bf16(a[2], a[3]); w.z = cvt_pk_bf16(b[0], b[1]); w.w = cvt_pk_bf16(b[2], b[3]);
;                         *(u32x4*)(KN + row * 512 + head * 64 + bj * 32 + fq * 8) = w; }
.LBB0_648:
	v_pk_mul_f32 v[26:27], v[14:15], v[14:15]
	v_pk_mul_f32 v[28:29], v[12:13], v[12:13]
	v_pk_mul_f32 v[30:31], v[10:11], v[10:11]
	v_pk_mul_f32 v[32:33], v[8:9], v[8:9]
	v_pk_mov_b32 v[38:39], v[28:29], v[26:27] op_sel:[1,0]
	v_mov_b32_e32 v29, v27
	v_pk_mov_b32 v[26:27], v[32:33], v[30:31] op_sel:[1,0]
	v_mov_b32_e32 v33, v31
	v_mul_f32_e32 v37, v0, v0
	v_mul_f32_e32 v34, v5, v5
	v_mul_f32_e32 v36, v7, v7
	v_pk_add_f32 v[28:29], v[38:39], v[28:29]
	v_pk_add_f32 v[26:27], v[26:27], v[32:33]
	v_mul_f32_e32 v40, v1, v1
	v_mul_f32_e32 v41, v2, v2
	v_mul_f32_e32 v42, v3, v3
	v_and_b32_e32 v44, 64, v157
	v_pk_fma_f32 v[30:31], v[4:5], v[4:5], v[34:35] op_sel_hi:[1,1,0]
	v_pk_fma_f32 v[34:35], v[6:7], v[6:7], v[36:37] op_sel_hi:[1,1,0]
	v_pk_add_f32 v[28:29], v[28:29], v[28:29] op_sel:[0,1] op_sel_hi:[1,0]
	v_pk_add_f32 v[26:27], v[26:27], v[26:27] op_sel:[0,1] op_sel_hi:[1,0]
	v_xor_b32_e32 v43, 16, v157
	v_add_u32_e32 v36, 64, v44
	v_mov_b32_e32 v31, v41
	v_mov_b32_e32 v35, v42
	v_mov_b32_e32 v29, v37
	v_mov_b32_e32 v27, v40
	v_cmp_lt_i32_e32 vcc, v43, v36
	v_pk_add_f32 v[30:31], v[30:31], v[34:35]
	v_pk_add_f32 v[26:27], v[28:29], v[26:27]
	v_cndmask_b32_e32 v32, v157, v43, vcc
	v_pk_add_f32 v[26:27], v[26:27], v[30:31]
	v_lshlrev_b32_e32 v32, 2, v32
	v_add_f32_e32 v26, v26, v27
	ds_bpermute_b32 v27, v32, v26
	v_xor_b32_e32 v28, 32, v157
	v_cmp_lt_i32_e32 vcc, v28, v36
	s_lshl_b32 s0, s48, 8
	v_lshlrev_b64 v[20:21], 10, v[20:21]
	v_cndmask_b32_e32 v28, v157, v28, vcc
	v_lshlrev_b32_e32 v28, 2, v28
	s_waitcnt lgkmcnt(0)
	v_add_f32_e32 v26, v26, v27
	ds_bpermute_b32 v27, v28, v26
	s_or_b32 s0, s0, s33
	v_lshl_add_u64 v[20:21], s[4:5], 0, v[20:21]
	s_ashr_i32 s1, s0, 31
	v_lshl_add_u64 v[20:21], s[0:1], 1, v[20:21]
	s_waitcnt lgkmcnt(0)
	v_add_f32_e32 v26, v26, v27
	v_fmamk_f32 v26, v26, 0x3c800000, v156
	v_mul_f32_e32 v27, 0x4b800000, v26
	v_cmp_gt_f32_e32 vcc, s13, v26
	s_nop 1
	v_cndmask_b32_e32 v26, v26, v27, vcc
	v_rsq_f32_e32 v28, v26
	v_lshl_add_u64 v[26:27], v[144:145], 1, v[20:21]
	v_mul_f32_e32 v29, 0x45800000, v28
	v_cndmask_b32_e32 v28, v28, v29, vcc
	v_pk_mul_f32 v[12:13], v[12:13], v[28:29] op_sel_hi:[1,0]
	v_pk_mul_f32 v[8:9], v[8:9], v[28:29] op_sel_hi:[1,0]
	v_pk_mul_f32 v[10:11], v[10:11], v[28:29] op_sel_hi:[1,0]
	v_pk_mul_f32 v[14:15], v[14:15], v[28:29] op_sel_hi:[1,0]
	v_pk_mul_f32 v[4:5], v[4:5], v[28:29] op_sel_hi:[1,0]
	v_pk_mul_f32 v[6:7], v[6:7], v[28:29] op_sel_hi:[1,0]
	v_pk_mul_f32 v[0:1], v[0:1], v[28:29] op_sel_hi:[1,0]
	v_pk_mul_f32 v[2:3], v[2:3], v[28:29] op_sel_hi:[1,0]
	v_pk_mul_f32 v[12:13], v[190:191], v[12:13]
	v_pk_mul_f32 v[16:17], v[196:197], v[10:11]
	v_pk_mul_f32 v[10:11], v[194:195], v[8:9]
	v_pk_mul_f32 v[14:15], v[192:193], v[14:15]
	v_cvt_pk_bf16_f32 v8, v12, v13
	v_cvt_pk_bf16_f32 v10, v10, v11
	v_cvt_pk_bf16_f32 v11, v16, v17
	v_lshl_add_u64 v[22:23], v[20:21], 0, 64
	v_cvt_pk_bf16_f32 v9, v14, v15
	global_store_dwordx4 v[26:27], v[8:11], off
	s_nop 0
	v_pk_mul_f32 v[6:7], v[200:201], v[6:7]
	v_pk_mul_f32 v[4:5], v[198:199], v[4:5]
	v_pk_mul_f32 v[2:3], v[204:205], v[2:3]
	v_pk_mul_f32 v[0:1], v[202:203], v[0:1]
	v_cvt_pk_bf16_f32 v16, v4, v5
	v_cvt_pk_bf16_f32 v17, v6, v7
	v_cvt_pk_bf16_f32 v19, v2, v3
	s_nop 0
	v_cvt_pk_bf16_f32 v18, v0, v1

; #define LAS __attribute__((address_space(3)))
; __device__ __forceinline__ float max3f(float a, float b, float c) { float r; asm("v_max3_f32 %0, %1, %2, %3" : "=v"(r) : "v"(a), "v"(b), "v"(c)); return r; }
; template <bool QK, bool SM>
; __device__ __forceinline__ void attn_step(const LAS unsigned char* kb, const LAS unsigned char* vbp, const bf16x8 (&qr)[6],
;                                           f32x16& s0, f32x16& s1, f32x16& o0, f32x16& o1, float& mrow, float& lsum) {
;     ...
;         for (int s = 0; s < 6; ++s) { const bf16x8 ka = *(const LAS bf16x8*)(kb + s * 32), kc = *(const LAS bf16x8*)(kb + 32 * KPITCH + s * 32);
;             n0 = __builtin_amdgcn_mfma_f32_32x32x16_bf16(ka, qr[s], n0, 0, 0, 0); n1 = __builtin_amdgcn_mfma_f32_32x32x16_bf16(kc, qr[s], n1, 0, 0, 0); }
;     }
;     if constexpr (SM) {
;         float mx = max3f(s0[0], s1[0], s0[1]); mx = max3f(mx, s1[1], s0[2]); float my = max3f(s1[2], s0[3], s1[3]);
; #pragma unroll
;         for (int r = 4; r < 16; r += 4) { mx = max3f(mx, s0[r], s1[r]); my = max3f(my, s0[r + 1], s1[r + 1]); mx = max3f(mx, s0[r + 2], s1[r + 2]); my = max3f(my, s0[r + 3], s1[r + 3]); }
;         mx = fmaxf(mx, my);
;         { const auto rr = __builtin_amdgcn_permlane32_swap(__float_as_uint(mx), __float_as_uint(mx), false, false); mx = fmaxf(__uint_as_float(rr[0]), __uint_as_float(rr[1])); }
;         const float mnew = fmaxf(mrow, mx), alpha = __builtin_amdgcn_exp2f(mrow - mnew); mrow = mnew;
;         const f32x2 m2 = (f32x2){mnew, mnew}; f32x2 ps2 = (f32x2){0.f, 0.f};
; #pragma unroll
;         for (int r = 0; r < 16; r += 2) { f32x2 a = (f32x2){s0[r], s0[r + 1]} - m2, b = (f32x2){s1[r], s1[r + 1]} - m2;
;             a.x = __builtin_amdgcn_exp2f(a.x); a.y = __builtin_amdgcn_exp2f(a.y); b.x = __builtin_amdgcn_exp2f(b.x); b.y = __builtin_amdgcn_exp2f(b.y);
;             s0[r] = a.x; s0[r + 1] = a.y; s1[r] = b.x; s1[r + 1] = b.y; ps2 += a + b; }
;         const float ps = ps2.x + ps2.y;
;         lsum = lsum * alpha + ps;
; #pragma unroll
;         for (int r = 0; r < 16; ++r) { o0[r] *= alpha; o1[r] *= alpha; }
.LBB0_952:
	ds_read_b128 v[2:5], v213 offset:13312
	ds_read_b128 v[10:13], v213 offset:13344
	ds_read_b128 v[80:83], v213 offset:19968
	ds_read_b128 v[96:99], v213 offset:20000
	ds_read_b128 v[84:87], v213 offset:13376
	ds_read_b128 v[88:91], v213 offset:13408
	s_waitcnt lgkmcnt(5)
	v_mfma_f32_32x32x16_bf16 v[112:127], v[2:5], v[164:167], 0
	ds_read_b128 v[100:103], v213 offset:20032
	ds_read_b128 v[104:107], v213 offset:20064
	ds_read_b128 v[92:95], v213 offset:13440
	ds_read_b128 v[108:111], v213 offset:13472
	ds_read_b128 v[6:9], v213 offset:20096
	ds_read_b128 v[2:5], v213 offset:20128
	v_max3_f32 v0, v48, v16, v49
	s_nop 0
	v_max3_f32 v0, v0, v17, v50
	s_nop 0
	v_max3_f32 v0, v0, v52, v20
	s_waitcnt lgkmcnt(10)
	v_mfma_f32_32x32x16_bf16 v[112:127], v[10:13], v[160:163], v[112:127]
	v_max3_f32 v10, v18, v51, v19
	v_max3_f32 v0, v0, v54, v22
	s_nop 0
	v_max3_f32 v10, v10, v53, v21
	v_max3_f32 v0, v0, v56, v24
	s_nop 0
	v_max3_f32 v10, v10, v55, v23
	s_waitcnt lgkmcnt(7)
	v_mfma_f32_32x32x16_bf16 v[112:127], v[84:87], v[156:159], v[112:127]
	v_max3_f32 v10, v10, v57, v25
	v_max3_f32 v0, v0, v58, v26
	s_nop 0
	v_max3_f32 v10, v10, v59, v27
	v_max3_f32 v0, v0, v60, v28
	s_nop 0
	v_max3_f32 v10, v10, v61, v29
	s_waitcnt lgkmcnt(6)
	v_mfma_f32_32x32x16_bf16 v[112:127], v[88:91], v[152:155], v[112:127]
	v_max3_f32 v10, v10, v63, v31
	v_max3_f32 v0, v0, v62, v30
	s_nop 0
	v_max_f32_e32 v10, v10, v10
	v_max_f32_e32 v0, v0, v0
	v_max_f32_e32 v0, v0, v10
	v_mov_b32_e32 v10, v0
	s_waitcnt lgkmcnt(3)
	v_mfma_f32_32x32x16_bf16 v[112:127], v[92:95], v[148:151], v[112:127]
	v_permlane32_swap_b32_e32 v0, v10
	v_max3_f32 v208, v206, v0, v10
	v_sub_f32_e32 v0, v206, v208
	v_exp_f32_e32 v0, v0
	v_sub_f32_e32 v10, v48, v208
	v_sub_f32_e32 v11, v49, v208
	v_sub_f32_e32 v12, v16, v208
	v_sub_f32_e32 v13, v17, v208
	v_mfma_f32_32x32x16_bf16 v[80:95], v[80:83], v[164:167], 0
	v_sub_f32_e32 v14, v50, v208
	v_sub_f32_e32 v15, v51, v208
	v_sub_f32_e32 v16, v18, v208
	v_sub_f32_e32 v17, v19, v208
	v_exp_f32_e32 v128, v10
	v_exp_f32_e32 v129, v11
	v_exp_f32_e32 v48, v12
	v_exp_f32_e32 v49, v13
	v_exp_f32_e32 v130, v14
	v_mfma_f32_32x32x16_bf16 v[80:95], v[96:99], v[160:163], v[80:95]
	v_exp_f32_e32 v131, v15
	v_exp_f32_e32 v50, v16
	v_exp_f32_e32 v51, v17
	v_add_f32_e32 v10, v128, v48
	v_add_f32_e32 v11, v129, v49
	v_sub_f32_e32 v16, v54, v208
	v_sub_f32_e32 v17, v55, v208
	v_add_f32_e32 v10, 0, v10
	v_add_f32_e32 v11, 0, v11
	v_add_f32_e32 v12, v130, v50
	v_add_f32_e32 v13, v131, v51
	v_mfma_f32_32x32x16_bf16 v[80:95], v[100:103], v[156:159], v[80:95]
	v_mul_f32_e32 v100, v36, v0
	v_mul_f32_e32 v101, v37, v0
	v_add_u32_e32 v36, v214, v204
	v_mul_f32_e32 v102, v38, v0
	v_mul_f32_e32 v103, v39, v0
	v_add_f32_e32 v10, v12, v10
	v_add_f32_e32 v11, v13, v11
	v_sub_f32_e32 v12, v52, v208
	v_sub_f32_e32 v13, v53, v208
	v_mul_f32_e32 v98, v34, v0
	v_mul_f32_e32 v99, v35, v0
	v_mul_f32_e32 v96, v32, v0
	v_mul_f32_e32 v97, v33, v0
	v_mfma_f32_32x32x16_bf16 v[80:95], v[104:107], v[152:155], v[80:95]
	v_mul_f32_e32 v106, v42, v0
	v_mul_f32_e32 v107, v43, v0
	v_mul_f32_e32 v104, v40, v0
	v_mul_f32_e32 v105, v41, v0
	v_exp_f32_e32 v12, v12
	v_exp_f32_e32 v13, v13
	v_exp_f32_e32 v16, v16
	v_exp_f32_e32 v17, v17
	v_cvt_pk_bf16_f32 v32, v128, v129
	s_waitcnt lgkmcnt(2)
	v_mfma_f32_32x32x16_bf16 v[112:127], v[108:111], v[144:147], v[112:127]
	v_mul_f32_e32 v110, v46, v0
	v_mul_f32_e32 v111, v47, v0
	v_add_u32_e32 v46, 0x6800, v36
	v_add_u32_e32 v47, 0x7800, v36
	ds_read2_b64 v[36:39], v47 offset0:32 offset1:34
	v_mul_f32_e32 v108, v44, v0
	v_mul_f32_e32 v109, v45, v0
	v_cvt_pk_bf16_f32 v33, v130, v131
	v_cvt_pk_bf16_f32 v34, v12, v13
	s_waitcnt lgkmcnt(2)
; #define LAS __attribute__((address_space(3)))
; __device__ __forceinline__ unsigned cvt_pk_bf16(float lo, float hi) { unsigned r; asm("v_cvt_pk_bf16_f32 %0, %1, %2" : "=v"(r) : "v"(lo), "v"(hi)); return r; }
; template <bool QK, bool SM>
; __device__ __forceinline__ void attn_step(const LAS unsigned char* kb, const LAS unsigned char* vbp, const bf16x8 (&qr)[6],
;                                           f32x16& s0, f32x16& s1, f32x16& o0, f32x16& o1, float& mrow, float& lsum) {
;     ...
;         for (int r = 0; r < 16; r += 2) { f32x2 a = (f32x2){s0[r], s0[r + 1]} - m2, b = (f32x2){s1[r], s1[r + 1]} - m2;
;             a.x = __builtin_amdgcn_exp2f(a.x); a.y = __builtin_amdgcn_exp2f(a.y); b.x = __builtin_amdgcn_exp2f(b.x); b.y = __builtin_amdgcn_exp2f(b.y);
;             s0[r] = a.x; s0[r + 1] = a.y; s1[r] = b.x; s1[r + 1] = b.y; ps2 += a + b; }
;         const float ps = ps2.x + ps2.y;
;         lsum = lsum * alpha + ps;
; #pragma unroll
;         for (int r = 0; r < 16; ++r) { o0[r] *= alpha; o1[r] *= alpha; }
;         bf16x8 pb[4];
; #pragma unroll
;         for (int S = 0; S < 4; ++S) { u32x4 w;
;             if (S < 2) { w.x = cvt_pk_bf16(s0[8 * S + 0], s0[8 * S + 1]); w.y = cvt_pk_bf16(s0[8 * S + 2], s0[8 * S + 3]); w.z = cvt_pk_bf16(s0[8 * S + 4], s0[8 * S + 5]); w.w = cvt_pk_bf16(s0[8 * S + 6], s0[8 * S + 7]); }
;             else { w.x = cvt_pk_bf16(s1[8 * S - 16], s1[8 * S - 15]); w.y = cvt_pk_bf16(s1[8 * S - 14], s1[8 * S - 13]); w.z = cvt_pk_bf16(s1[8 * S - 12], s1[8 * S - 11]); w.w = cvt_pk_bf16(s1[8 * S - 10], s1[8 * S - 9]); }
;             pb[S] = __builtin_bit_cast(bf16x8, w); }
; #pragma unroll
;         for (int S = 0; S < 4; ++S) {
;             const u32x2 a0 = *(const LAS u32x2*)(vbp + S * 32), a1 = *(const LAS u32x2*)(vbp + S * 32 + 16);
;             const u32x2 c0 = *(const LAS u32x2*)(vbp + 32 * VPITCH + S * 32), c1 = *(const LAS u32x2*)(vbp + 32 * VPITCH + S * 32 + 16);
;             const bf16x8 va = __builtin_bit_cast(bf16x8, (u32x4){a0.x, a0.y, a1.x, a1.y}), vc = __builtin_bit_cast(bf16x8, (u32x4){c0.x, c0.y, c1.x, c1.y});
;             o0 = __builtin_amdgcn_mfma_f32_32x32x16_bf16(va, pb[S], o0, 0, 0, 0); o1 = __builtin_amdgcn_mfma_f32_32x32x16_bf16(vc, pb[S], o1, 0, 0, 0); }
	v_mfma_f32_32x32x16_bf16 v[80:95], v[6:9], v[148:151], v[80:95]
	ds_read2_b64 v[6:9], v46 offset1:2
	v_cvt_pk_bf16_f32 v35, v16, v17
	v_mul_f32_e32 v142, v78, v0
	v_mul_f32_e32 v143, v79, v0
	v_mul_f32_e32 v140, v76, v0
	v_mul_f32_e32 v141, v77, v0
	v_mul_f32_e32 v138, v74, v0
	v_mul_f32_e32 v139, v75, v0
	v_mul_f32_e32 v136, v72, v0
	v_mul_f32_e32 v137, v73, v0
	v_mul_f32_e32 v134, v70, v0
	v_mul_f32_e32 v135, v71, v0
	s_waitcnt lgkmcnt(0)
	v_mfma_f32_32x32x16_bf16 v[96:111], v[6:9], v[32:35], v[96:111]
	ds_read2_b64 v[6:9], v46 offset0:4 offset1:6
	v_mul_f32_e32 v132, v68, v0
	v_mul_f32_e32 v133, v69, v0
	v_mul_f32_e32 v130, v66, v0
	v_mul_f32_e32 v131, v67, v0
	v_mul_f32_e32 v128, v64, v0
	v_mul_f32_e32 v129, v65, v0
	v_sub_f32_e32 v14, v20, v208
	v_sub_f32_e32 v15, v21, v208
	v_sub_f32_e32 v18, v56, v208
	v_sub_f32_e32 v19, v57, v208
	v_sub_f32_e32 v20, v58, v208
	v_sub_f32_e32 v21, v59, v208
	v_mfma_f32_32x32x16_bf16 v[128:143], v[36:39], v[32:35], v[128:143]
	ds_read2_b64 v[36:39], v47 offset0:36 offset1:38
	v_sub_f32_e32 v52, v60, v208
	v_sub_f32_e32 v53, v61, v208
	v_sub_f32_e32 v54, v62, v208
	v_sub_f32_e32 v55, v63, v208
	v_exp_f32_e32 v18, v18
	v_exp_f32_e32 v19, v19
	v_exp_f32_e32 v20, v20
	v_exp_f32_e32 v21, v21
	v_exp_f32_e32 v52, v52
	v_exp_f32_e32 v53, v53
	v_exp_f32_e32 v40, v54
	v_exp_f32_e32 v41, v55
	v_cvt_pk_bf16_f32 v32, v18, v19
	v_cvt_pk_bf16_f32 v33, v20, v21
	v_cvt_pk_bf16_f32 v34, v52, v53
	v_cvt_pk_bf16_f32 v35, v40, v41
	v_exp_f32_e32 v14, v14
	s_waitcnt lgkmcnt(1)
	v_mfma_f32_32x32x16_bf16 v[96:111], v[6:9], v[32:35], v[96:111]
	v_sub_f32_e32 v6, v22, v208
	v_sub_f32_e32 v7, v23, v208
	v_sub_f32_e32 v22, v24, v208
	v_sub_f32_e32 v23, v25, v208
	v_exp_f32_e32 v42, v6
	v_exp_f32_e32 v43, v7
	ds_read2_b64 v[6:9], v46 offset0:8 offset1:10
	v_exp_f32_e32 v15, v15
	v_exp_f32_e32 v44, v22
	s_waitcnt lgkmcnt(1)
	v_mfma_f32_32x32x16_bf16 v[128:143], v[36:39], v[32:35], v[128:143]
	ds_read2_b64 v[32:35], v47 offset0:40 offset1:42
	v_exp_f32_e32 v45, v23
	v_sub_f32_e32 v26, v26, v208
	v_sub_f32_e32 v27, v27, v208
	v_cvt_pk_bf16_f32 v22, v48, v49
	v_cvt_pk_bf16_f32 v23, v50, v51
	v_cvt_pk_bf16_f32 v24, v14, v15
	v_cvt_pk_bf16_f32 v25, v42, v43
	v_mfma_f32_32x32x16_bf16 v[80:95], v[2:5], v[144:147], v[80:95]
	v_exp_f32_e32 v36, v26
	v_exp_f32_e32 v37, v27
	v_sub_f32_e32 v26, v30, v208
	v_sub_f32_e32 v27, v31, v208
	s_nop 0
	v_exp_f32_e32 v30, v26
	v_exp_f32_e32 v31, v27
	s_waitcnt lgkmcnt(1)
	v_mfma_f32_32x32x16_bf16 v[96:111], v[6:9], v[22:25], v[96:111]
	v_sub_f32_e32 v6, v28, v208
	v_sub_f32_e32 v7, v29, v208
	ds_read2_b64 v[26:29], v47 offset0:44 offset1:46
	v_exp_f32_e32 v38, v6
	v_exp_f32_e32 v39, v7
	ds_read2_b64 v[6:9], v46 offset0:12 offset1:14
	s_waitcnt lgkmcnt(2)
	v_mfma_f32_32x32x16_bf16 v[128:143], v[32:35], v[22:25], v[128:143]
	v_cvt_pk_bf16_f32 v22, v44, v45
	v_cvt_pk_bf16_f32 v23, v36, v37
	v_cvt_pk_bf16_f32 v24, v38, v39
	v_cvt_pk_bf16_f32 v25, v30, v31
	s_waitcnt lgkmcnt(0)
	v_mfma_f32_32x32x16_bf16 v[96:111], v[6:9], v[22:25], v[96:111]
	v_add_f32_e32 v6, v12, v14
	v_add_f32_e32 v7, v13, v15
	v_add_f32_e32 v8, v16, v42
	v_add_f32_e32 v9, v17, v43
	v_add_f32_e32 v6, v6, v10
	v_add_f32_e32 v7, v7, v11
	v_add_f32_e32 v6, v8, v6
	v_add_f32_e32 v7, v9, v7
	v_add_f32_e32 v8, v18, v44
	v_add_f32_e32 v9, v19, v45
	v_mfma_f32_32x32x16_bf16 v[128:143], v[26:29], v[22:25], v[128:143]
	v_add_f32_e32 v6, v8, v6
	v_add_f32_e32 v7, v9, v7
	v_add_f32_e32 v8, v20, v36
	v_add_f32_e32 v9, v21, v37
	v_add_f32_e32 v6, v8, v6
	v_add_f32_e32 v7, v9, v7
	v_add_f32_e32 v8, v52, v38
	v_add_f32_e32 v9, v53, v39
	s_nop 0
	v_add_f32_e32 v6, v8, v6
	v_add_f32_e32 v7, v9, v7
	v_add_f32_e32 v8, v40, v30
	v_add_f32_e32 v9, v41, v31
	s_nop 0
	v_add_f32_e32 v6, v8, v6
	v_add_f32_e32 v7, v9, v7
	s_nop 0
	v_add_f32_e32 v216, v6, v7
	v_fmac_f32_e32 v216, v215, v0
	s_waitcnt vmcnt(5)
	ds_write_b128 v197, v[168:171]
	s_and_saveexec_b64 s[10:11], s[0:1]
	s_cbranch_execnz .LBB0_944
	s_branch .LBB0_945

; #define LAS __attribute__((address_space(3)))
; __device__ __forceinline__ float max3f(float a, float b, float c) { float r; asm("v_max3_f32 %0, %1, %2, %3" : "=v"(r) : "v"(a), "v"(b), "v"(c)); return r; }
; template <bool QK, bool SM>
; __device__ __forceinline__ void attn_step(const LAS unsigned char* kb, const LAS unsigned char* vbp, const bf16x8 (&qr)[6],
;                                           f32x16& s0, f32x16& s1, f32x16& o0, f32x16& o1, float& mrow, float& lsum) {
;     ...
;         for (int s = 0; s < 6; ++s) { const bf16x8 ka = *(const LAS bf16x8*)(kb + s * 32), kc = *(const LAS bf16x8*)(kb + 32 * KPITCH + s * 32);
;             n0 = __builtin_amdgcn_mfma_f32_32x32x16_bf16(ka, qr[s], n0, 0, 0, 0); n1 = __builtin_amdgcn_mfma_f32_32x32x16_bf16(kc, qr[s], n1, 0, 0, 0); }
;     }
;     if constexpr (SM) {
;         float mx = max3f(s0[0], s1[0], s0[1]); mx = max3f(mx, s1[1], s0[2]); float my = max3f(s1[2], s0[3], s1[3]);
; #pragma unroll
;         for (int r = 4; r < 16; r += 4) { mx = max3f(mx, s0[r], s1[r]); my = max3f(my, s0[r + 1], s1[r + 1]); mx = max3f(mx, s0[r + 2], s1[r + 2]); my = max3f(my, s0[r + 3], s1[r + 3]); }
;         mx = fmaxf(mx, my);
;         { const auto rr = __builtin_amdgcn_permlane32_swap(__float_as_uint(mx), __float_as_uint(mx), false, false); mx = fmaxf(__uint_as_float(rr[0]), __uint_as_float(rr[1])); }
;         const float mnew = fmaxf(mrow, mx), alpha = __builtin_amdgcn_exp2f(mrow - mnew); mrow = mnew;
;         const f32x2 m2 = (f32x2){mnew, mnew}; f32x2 ps2 = (f32x2){0.f, 0.f};
; #pragma unroll
;         for (int r = 0; r < 16; r += 2) { f32x2 a = (f32x2){s0[r], s0[r + 1]} - m2, b = (f32x2){s1[r], s1[r + 1]} - m2;
;             a.x = __builtin_amdgcn_exp2f(a.x); a.y = __builtin_amdgcn_exp2f(a.y); b.x = __builtin_amdgcn_exp2f(b.x); b.y = __builtin_amdgcn_exp2f(b.y);
;             s0[r] = a.x; s0[r + 1] = a.y; s1[r] = b.x; s1[r + 1] = b.y; ps2 += a + b; }
;         const float ps = ps2.x + ps2.y;
;         lsum = lsum * alpha + ps;
; #pragma unroll
;         for (int r = 0; r < 16; ++r) { o0[r] *= alpha; o1[r] *= alpha; }
.LBB0_957:
	ds_read_b128 v[2:5], v213
	ds_read_b128 v[10:13], v213 offset:32
	ds_read_b128 v[14:17], v213 offset:6656
	ds_read_b128 v[32:35], v213 offset:6688
	ds_read_b128 v[18:21], v213 offset:64
	ds_read_b128 v[22:25], v213 offset:96
	s_waitcnt lgkmcnt(5)
	v_mfma_f32_32x32x16_bf16 v[48:63], v[2:5], v[164:167], 0
	v_max3_f32 v0, v112, v80, v113
	ds_read_b128 v[36:39], v213 offset:6720
	ds_read_b128 v[40:43], v213 offset:6752
	ds_read_b128 v[26:29], v213 offset:128
	ds_read_b128 v[44:47], v213 offset:160
	ds_read_b128 v[6:9], v213 offset:6784
	ds_read_b128 v[2:5], v213 offset:6816
	v_max3_f32 v0, v0, v81, v114
	v_add_u32_e32 v68, v214, v204
	v_max3_f32 v0, v0, v116, v84
	s_nop 0
	v_max3_f32 v0, v0, v118, v86
	s_waitcnt lgkmcnt(10)
	v_mfma_f32_32x32x16_bf16 v[48:63], v[10:13], v[160:163], v[48:63]
	v_max3_f32 v10, v82, v115, v83
	v_max3_f32 v0, v0, v120, v88
	s_nop 0
	v_max3_f32 v10, v10, v117, v85
	v_max3_f32 v0, v0, v122, v90
	s_nop 0
	v_max3_f32 v10, v10, v119, v87
	s_waitcnt lgkmcnt(7)
	v_mfma_f32_32x32x16_bf16 v[48:63], v[18:21], v[156:159], v[48:63]
	v_max3_f32 v10, v10, v121, v89
	v_max3_f32 v0, v0, v124, v92
	s_nop 0
	v_max3_f32 v10, v10, v123, v91
	v_max3_f32 v0, v0, v126, v94
	s_nop 0
	v_max3_f32 v10, v10, v125, v93
	s_waitcnt lgkmcnt(6)
	v_mfma_f32_32x32x16_bf16 v[48:63], v[22:25], v[152:155], v[48:63]
	v_max3_f32 v10, v10, v127, v95
	v_max_f32_e32 v0, v0, v0
	v_max_f32_e32 v10, v10, v10
	v_max_f32_e32 v0, v0, v10
	v_mov_b32_e32 v10, v0
	s_nop 1
	v_permlane32_swap_b32_e32 v0, v10
	v_max3_f32 v206, v208, v0, v10
	v_sub_f32_e32 v18, v114, v206
	v_sub_f32_e32 v19, v115, v206
	v_sub_f32_e32 v20, v82, v206
	v_sub_f32_e32 v21, v83, v206
	s_waitcnt lgkmcnt(3)
	v_mfma_f32_32x32x16_bf16 v[48:63], v[26:29], v[148:151], v[48:63]
	v_exp_f32_e32 v66, v18
	v_exp_f32_e32 v67, v19
	v_exp_f32_e32 v114, v20
	v_exp_f32_e32 v115, v21
	v_sub_f32_e32 v0, v208, v206
	v_exp_f32_e32 v0, v0
	v_sub_f32_e32 v10, v112, v206
	v_sub_f32_e32 v11, v113, v206
	v_mfma_f32_32x32x16_bf16 v[16:31], v[14:17], v[164:167], 0
	v_sub_f32_e32 v12, v80, v206
	v_sub_f32_e32 v13, v81, v206
	v_exp_f32_e32 v64, v10
	v_exp_f32_e32 v65, v11
	v_exp_f32_e32 v112, v12
	v_exp_f32_e32 v113, v13
	v_add_f32_e32 v12, v66, v114
	v_add_f32_e32 v13, v67, v115
	v_sub_f32_e32 v14, v84, v206
	v_sub_f32_e32 v15, v85, v206
	v_mfma_f32_32x32x16_bf16 v[16:31], v[32:35], v[160:163], v[16:31]
	v_sub_f32_e32 v32, v118, v206
	v_sub_f32_e32 v33, v119, v206
	v_add_f32_e32 v10, v64, v112
	v_add_f32_e32 v11, v65, v113
	v_exp_f32_e32 v80, v32
	v_exp_f32_e32 v81, v33
	v_sub_f32_e32 v32, v120, v206
	v_sub_f32_e32 v33, v121, v206
	v_add_f32_e32 v10, 0, v10
	v_add_f32_e32 v11, 0, v11
	v_exp_f32_e32 v82, v32
	v_mfma_f32_32x32x16_bf16 v[16:31], v[36:39], v[156:159], v[16:31]
	v_mul_f32_e32 v38, v102, v0
	v_mul_f32_e32 v39, v103, v0
	v_mul_f32_e32 v36, v100, v0
	v_mul_f32_e32 v37, v101, v0
	v_exp_f32_e32 v83, v33
	v_sub_f32_e32 v32, v122, v206
	v_sub_f32_e32 v33, v123, v206
	v_add_f32_e32 v10, v12, v10
	v_add_f32_e32 v11, v13, v11
	v_exp_f32_e32 v84, v32
	v_exp_f32_e32 v85, v33
	v_mfma_f32_32x32x16_bf16 v[16:31], v[40:43], v[152:155], v[16:31]
	v_sub_f32_e32 v32, v124, v206
	v_sub_f32_e32 v33, v125, v206
	v_sub_f32_e32 v12, v116, v206
	v_sub_f32_e32 v13, v117, v206
	v_exp_f32_e32 v116, v32
	v_exp_f32_e32 v117, v33
	v_mul_f32_e32 v42, v106, v0
	v_mul_f32_e32 v43, v107, v0
	v_mul_f32_e32 v40, v104, v0
	v_mul_f32_e32 v41, v105, v0
	v_mul_f32_e32 v34, v98, v0
	v_mul_f32_e32 v35, v99, v0
	s_waitcnt lgkmcnt(2)
	v_mfma_f32_32x32x16_bf16 v[48:63], v[44:47], v[144:147], v[48:63]
	v_mul_f32_e32 v46, v110, v0
	v_mul_f32_e32 v47, v111, v0
	v_add_u32_e32 v110, 0x8800, v68
	v_add_u32_e32 v111, 0x9800, v68
	ds_read2_b64 v[100:103], v111 offset0:96 offset1:98
	v_mul_f32_e32 v44, v108, v0
	v_mul_f32_e32 v45, v109, v0
	v_mul_f32_e32 v32, v96, v0
	v_mul_f32_e32 v33, v97, v0
	v_exp_f32_e32 v12, v12
	s_waitcnt lgkmcnt(2)
; #define LAS __attribute__((address_space(3)))
; __device__ __forceinline__ unsigned cvt_pk_bf16(float lo, float hi) { unsigned r; asm("v_cvt_pk_bf16_f32 %0, %1, %2" : "=v"(r) : "v"(lo), "v"(hi)); return r; }
; template <bool QK, bool SM>
; __device__ __forceinline__ void attn_step(const LAS unsigned char* kb, const LAS unsigned char* vbp, const bf16x8 (&qr)[6],
;                                           f32x16& s0, f32x16& s1, f32x16& o0, f32x16& o1, float& mrow, float& lsum) {
;     ...
;         bf16x8 pb[4];
; #pragma unroll
;         for (int S = 0; S < 4; ++S) { u32x4 w;
;             if (S < 2) { w.x = cvt_pk_bf16(s0[8 * S + 0], s0[8 * S + 1]); w.y = cvt_pk_bf16(s0[8 * S + 2], s0[8 * S + 3]); w.z = cvt_pk_bf16(s0[8 * S + 4], s0[8 * S + 5]); w.w = cvt_pk_bf16(s0[8 * S + 6], s0[8 * S + 7]); }
;             else { w.x = cvt_pk_bf16(s1[8 * S - 16], s1[8 * S - 15]); w.y = cvt_pk_bf16(s1[8 * S - 14], s1[8 * S - 13]); w.z = cvt_pk_bf16(s1[8 * S - 12], s1[8 * S - 11]); w.w = cvt_pk_bf16(s1[8 * S - 10], s1[8 * S - 9]); }
;             pb[S] = __builtin_bit_cast(bf16x8, w); }
; #pragma unroll
;         for (int S = 0; S < 4; ++S) {
;             const u32x2 a0 = *(const LAS u32x2*)(vbp + S * 32), a1 = *(const LAS u32x2*)(vbp + S * 32 + 16);
;             const u32x2 c0 = *(const LAS u32x2*)(vbp + 32 * VPITCH + S * 32), c1 = *(const LAS u32x2*)(vbp + 32 * VPITCH + S * 32 + 16);
;             const bf16x8 va = __builtin_bit_cast(bf16x8, (u32x4){a0.x, a0.y, a1.x, a1.y}), vc = __builtin_bit_cast(bf16x8, (u32x4){c0.x, c0.y, c1.x, c1.y});
;             o0 = __builtin_amdgcn_mfma_f32_32x32x16_bf16(va, pb[S], o0, 0, 0, 0); o1 = __builtin_amdgcn_mfma_f32_32x32x16_bf16(vc, pb[S], o1, 0, 0, 0); }
	v_mfma_f32_32x32x16_bf16 v[16:31], v[6:9], v[148:151], v[16:31]
	ds_read2_b64 v[6:9], v110 offset0:64 offset1:66
	v_exp_f32_e32 v13, v13
	v_cvt_pk_bf16_f32 v96, v64, v65
	v_cvt_pk_bf16_f32 v97, v66, v67
	v_cvt_pk_bf16_f32 v98, v12, v13
	v_cvt_pk_bf16_f32 v99, v80, v81
	v_mul_f32_e32 v78, v142, v0
	v_mul_f32_e32 v79, v143, v0
	s_waitcnt lgkmcnt(0)
	v_mfma_f32_32x32x16_bf16 v[32:47], v[6:9], v[96:99], v[32:47]
	ds_read2_b64 v[6:9], v110 offset0:68 offset1:70
	v_mul_f32_e32 v76, v140, v0
	v_mul_f32_e32 v77, v141, v0
	v_mul_f32_e32 v74, v138, v0
	v_mul_f32_e32 v75, v139, v0
	v_mul_f32_e32 v72, v136, v0
	v_mul_f32_e32 v73, v137, v0
	v_mul_f32_e32 v70, v134, v0
	v_mul_f32_e32 v71, v135, v0
	v_mul_f32_e32 v68, v132, v0
	v_mul_f32_e32 v69, v133, v0
	v_mul_f32_e32 v66, v130, v0
	v_mul_f32_e32 v67, v131, v0
	v_mul_f32_e32 v64, v128, v0
	v_mul_f32_e32 v65, v129, v0
	v_sub_f32_e32 v118, v126, v206
	v_sub_f32_e32 v119, v127, v206
	v_exp_f32_e32 v14, v14
	v_mfma_f32_32x32x16_bf16 v[64:79], v[100:103], v[96:99], v[64:79]
	ds_read2_b64 v[100:103], v111 offset0:100 offset1:102
	v_exp_f32_e32 v104, v118
	v_exp_f32_e32 v105, v119
	v_cvt_pk_bf16_f32 v96, v82, v83
	v_cvt_pk_bf16_f32 v97, v84, v85
	v_cvt_pk_bf16_f32 v98, v116, v117
	v_cvt_pk_bf16_f32 v99, v104, v105
	v_exp_f32_e32 v15, v15
	s_waitcnt lgkmcnt(1)
	v_mfma_f32_32x32x16_bf16 v[32:47], v[6:9], v[96:99], v[32:47]
	v_sub_f32_e32 v6, v86, v206
	v_sub_f32_e32 v7, v87, v206
	v_sub_f32_e32 v86, v88, v206
	v_sub_f32_e32 v87, v89, v206
	v_exp_f32_e32 v106, v6
	v_exp_f32_e32 v107, v7
	ds_read2_b64 v[6:9], v110 offset0:72 offset1:74
	v_exp_f32_e32 v108, v86
	v_exp_f32_e32 v109, v87
	s_waitcnt lgkmcnt(1)
	v_mfma_f32_32x32x16_bf16 v[64:79], v[100:103], v[96:99], v[64:79]
	ds_read2_b64 v[96:99], v111 offset0:104 offset1:106
	v_sub_f32_e32 v90, v90, v206
	v_sub_f32_e32 v91, v91, v206
	v_cvt_pk_bf16_f32 v86, v112, v113
	v_cvt_pk_bf16_f32 v87, v114, v115
	v_cvt_pk_bf16_f32 v88, v14, v15
	v_cvt_pk_bf16_f32 v89, v106, v107
	s_waitcnt lgkmcnt(1)
	v_mfma_f32_32x32x16_bf16 v[32:47], v[6:9], v[86:89], v[32:47]
	v_sub_f32_e32 v6, v92, v206
	v_sub_f32_e32 v7, v93, v206
	v_exp_f32_e32 v100, v90
	v_exp_f32_e32 v101, v91
	v_exp_f32_e32 v102, v6
	v_exp_f32_e32 v103, v7
	v_sub_f32_e32 v90, v94, v206
	v_sub_f32_e32 v91, v95, v206
	ds_read2_b64 v[6:9], v110 offset0:76 offset1:78
	v_exp_f32_e32 v94, v90
	v_exp_f32_e32 v95, v91
	ds_read2_b64 v[90:93], v111 offset0:108 offset1:110
	s_waitcnt lgkmcnt(2)
	v_mfma_f32_32x32x16_bf16 v[64:79], v[96:99], v[86:89], v[64:79]
	v_cvt_pk_bf16_f32 v86, v108, v109
	v_cvt_pk_bf16_f32 v87, v100, v101
	v_cvt_pk_bf16_f32 v88, v102, v103
	v_cvt_pk_bf16_f32 v89, v94, v95
	s_waitcnt lgkmcnt(1)
	v_mfma_f32_32x32x16_bf16 v[32:47], v[6:9], v[86:89], v[32:47]
	v_add_f32_e32 v6, v12, v14
	v_add_f32_e32 v7, v13, v15
	v_add_f32_e32 v8, v80, v106
	v_add_f32_e32 v9, v81, v107
	v_add_f32_e32 v6, v6, v10
	v_add_f32_e32 v7, v7, v11
	v_add_f32_e32 v6, v8, v6
	v_add_f32_e32 v7, v9, v7
	v_add_f32_e32 v8, v82, v108
	v_add_f32_e32 v9, v83, v109
	s_waitcnt lgkmcnt(0)
	v_mfma_f32_32x32x16_bf16 v[64:79], v[90:93], v[86:89], v[64:79]
	v_add_f32_e32 v6, v8, v6
	v_add_f32_e32 v7, v9, v7
	v_add_f32_e32 v8, v84, v100
	v_add_f32_e32 v9, v85, v101
	v_add_f32_e32 v6, v8, v6
	v_add_f32_e32 v7, v9, v7
	v_add_f32_e32 v8, v116, v102
	v_add_f32_e32 v9, v117, v103
	s_nop 0
	v_add_f32_e32 v6, v8, v6
	v_add_f32_e32 v7, v9, v7
	v_mfma_f32_32x32x16_bf16 v[16:31], v[2:5], v[144:147], v[16:31]
	v_add_f32_e32 v8, v104, v94
	v_add_f32_e32 v9, v105, v95
	v_add_f32_e32 v6, v8, v6
	v_add_f32_e32 v7, v9, v7
	v_add_f32_e32 v215, v6, v7
	v_fmac_f32_e32 v215, v216, v0
	s_waitcnt vmcnt(5)
	ds_write_b128 v197, v[184:187] offset:13312
	s_and_saveexec_b64 s[10:11], s[0:1]
	s_cbranch_execz .LBB0_940

; __device__ __forceinline__ unsigned cvt_pk_bf16(float lo, float hi) { unsigned r; asm("v_cvt_pk_bf16_f32 %0, %1, %2" : "=v"(r) : "v"(lo), "v"(hi)); return r; }
; #define FRESH_IDS() const int tid = fresh_tid(), lane = tid & 63, wid = __builtin_amdgcn_readfirstlane(tid >> 6); (void)tid; (void)lane; (void)wid
; __device__ __forceinline__ void norm_apply(const f32x4 (&v)[4], const float* g, const float* sc, const float* sh, bf16_t* orow, int lane) {
;     float s = 0.f;
; #pragma unroll
;     for (int j = 0; j < 4; ++j) s += (v[j][0] * v[j][0] + v[j][1] * v[j][1]) + (v[j][2] * v[j][2] + v[j][3] * v[j][3]);
;     const float rstd = rsqrtf(wave_sum(s) * (1.f / 1024.f) + EPS);
; #pragma unroll
;     for (int j = 0; j < 4; ++j) { const int c4 = lane + 64 * j;
;         const f32x4 gg = *((const f32x4*)g + c4), cc = *((const f32x4*)sc + c4), hh = *((const f32x4*)sh + c4);
;         const f32x4 h = v[j] * rstd * gg * (cc + 1.f) + hh;
;         u32x2 w; w.x = cvt_pk_bf16(h[0], h[1]); w.y = cvt_pk_bf16(h[2], h[3]);
;         *((u32x2*)orow + c4) = w; }
; __global__ void __launch_bounds__(512, 2) mega_fwd(Args a) {
;     ...
;     { FRESH_IDS();
;         int row = bx * 8 + wid; f32x4 nv[4];
;         if (row < MP) row_load_bf16(X1B + (size_t)row * DM, nv, lane);
;         for (; row < MP; row += G * 8) {
;             f32x4 v[4];
; #pragma unroll
;             for (int j = 0; j < 4; ++j) v[j] = nv[j];
;             const int nr = row + G * 8;
;             if (nr < MP) row_load_bf16(X1B + (size_t)nr * DM, nv, lane);
;             const int b16 = row >> 12;
;             norm_apply(v, norm2_g, MOD + (size_t)b16 * 6144 + 4096, MOD + (size_t)b16 * 6144 + 3072, Hb + (size_t)row * DM, lane);
.LBB0_1100:
	s_or_b64 exec, exec, s[0:1]
	s_waitcnt lgkmcnt(0)
	v_mov_b32_e32 v0, v211
	s_barrier
	s_nop 0
	v_readfirstlane_b32 s0, v0
	s_ashr_i32 s7, s0, 6
	v_readlane_b32 s0, v238, 46
	v_and_b32_e32 v4, 63, v0
	s_add_i32 s26, s7, s0
	s_cmpk_gt_i32 s26, 0x7fff
	v_lshlrev_b32_e32 v10, 3, v4
	v_lshlrev_b32_e32 v0, 4, v4
	v_or_b32_e32 v6, 64, v4
	s_cbranch_scc1 .LBB0_1105
	v_readlane_b32 s46, v238, 30
	v_readlane_b32 s47, v238, 31
	v_lshlrev_b32_e32 v1, 5, v4
	v_xor_b32_e32 v2, 1, v4
	v_lshlrev_b32_e32 v2, 2, v2
	v_xor_b32_e32 v3, 2, v4
	v_lshlrev_b32_e32 v3, 2, v3
	v_xor_b32_e32 v5, 4, v4
	v_lshlrev_b32_e32 v5, 2, v5
	v_xor_b32_e32 v7, 8, v4
	v_lshlrev_b32_e32 v7, 2, v7
	v_xor_b32_e32 v8, 16, v4
	v_lshlrev_b32_e32 v8, 2, v8
	v_xor_b32_e32 v9, 32, v4
	v_lshlrev_b32_e32 v9, 2, v9
	global_load_dwordx4 v[16:19], v1, s[46:47]
	global_load_dwordx4 v[20:23], v1, s[46:47] offset:16
	global_load_dwordx4 v[24:27], v1, s[46:47] offset:2048
	global_load_dwordx4 v[28:31], v1, s[46:47] offset:2064
	s_lshr_b32 s23, s26, 12
	s_mul_i32 s23, s23, 0x6000
	s_add_u32 s8, s30, s23
	s_addc_u32 s9, s31, 0
	s_add_u32 s10, s8, 0x4000
	s_addc_u32 s11, s9, 0
	s_add_u32 s8, s8, 0x3000
	s_addc_u32 s9, s9, 0
	global_load_dwordx4 v[32:35], v1, s[10:11]
	global_load_dwordx4 v[36:39], v1, s[10:11] offset:16
	global_load_dwordx4 v[40:43], v1, s[10:11] offset:2048
	global_load_dwordx4 v[44:47], v1, s[10:11] offset:2064
	global_load_dwordx4 v[48:51], v1, s[8:9]
	global_load_dwordx4 v[52:55], v1, s[8:9] offset:16
	global_load_dwordx4 v[56:59], v1, s[8:9] offset:2048
	global_load_dwordx4 v[60:63], v1, s[8:9] offset:2064
	s_lshl_b32 s0, s26, 11
	s_add_u32 s0, s4, s0
	s_addc_u32 s1, s5, 0
	global_load_dwordx4 v[96:99], v0, s[0:1]
	global_load_dwordx4 v[100:103], v0, s[0:1] offset:1024
	s_add_i32 s22, s26, s88
	s_min_i32 s22, s22, 0x7fff
	s_lshl_b32 s0, s22, 11
	s_add_u32 s0, s4, s0
	s_addc_u32 s1, s5, 0
	global_load_dwordx4 v[104:107], v0, s[0:1]
	global_load_dwordx4 v[108:111], v0, s[0:1] offset:1024
	s_add_i32 s22, s26, s88
	s_min_i32 s22, s22, 0x7fff
	s_lshr_b32 s23, s22, 12
	s_mul_i32 s23, s23, 0x6000
	s_add_u32 s8, s30, s23
	s_addc_u32 s9, s31, 0
	s_add_u32 s10, s8, 0x4000
	s_addc_u32 s11, s9, 0
	s_add_u32 s8, s8, 0x3000
	s_addc_u32 s9, s9, 0
	global_load_dwordx4 v[64:67], v1, s[10:11]
	global_load_dwordx4 v[68:71], v1, s[10:11] offset:16
	global_load_dwordx4 v[72:75], v1, s[10:11] offset:2048
	global_load_dwordx4 v[76:79], v1, s[10:11] offset:2064
	global_load_dwordx4 v[80:83], v1, s[8:9]
	global_load_dwordx4 v[84:87], v1, s[8:9] offset:16
	global_load_dwordx4 v[88:91], v1, s[8:9] offset:2048
	global_load_dwordx4 v[92:95], v1, s[8:9] offset:2064
	s_waitcnt vmcnt(10)
	s_branch .Lp6_even_go
.Lp6_even:
	s_add_i32 s22, s26, s88
	s_min_i32 s22, s22, 0x7fff
	s_lshr_b32 s23, s22, 12
	s_mul_i32 s23, s23, 0x6000
	s_add_u32 s8, s30, s23
	s_addc_u32 s9, s31, 0
	s_add_u32 s10, s8, 0x4000
	s_addc_u32 s11, s9, 0
	s_add_u32 s8, s8, 0x3000
	s_addc_u32 s9, s9, 0
	global_load_dwordx4 v[64:67], v1, s[10:11]
	global_load_dwordx4 v[68:71], v1, s[10:11] offset:16
	global_load_dwordx4 v[72:75], v1, s[10:11] offset:2048
	global_load_dwordx4 v[76:79], v1, s[10:11] offset:2064
	global_load_dwordx4 v[80:83], v1, s[8:9]
	global_load_dwordx4 v[84:87], v1, s[8:9] offset:16
	global_load_dwordx4 v[88:91], v1, s[8:9] offset:2048
	global_load_dwordx4 v[92:95], v1, s[8:9] offset:2064
	s_waitcnt vmcnt(12)
.Lp6_even_go:
	v_lshlrev_b32_e32 v120, 16, v96
	v_and_b32_e32 v121, 0xffff0000, v96
	v_lshlrev_b32_e32 v122, 16, v97
	v_and_b32_e32 v123, 0xffff0000, v97
	v_lshlrev_b32_e32 v124, 16, v98
	v_and_b32_e32 v125, 0xffff0000, v98
	v_lshlrev_b32_e32 v126, 16, v99
	v_and_b32_e32 v127, 0xffff0000, v99
	v_lshlrev_b32_e32 v128, 16, v100
	v_and_b32_e32 v129, 0xffff0000, v100
	v_lshlrev_b32_e32 v130, 16, v101
	v_and_b32_e32 v131, 0xffff0000, v101
	v_lshlrev_b32_e32 v132, 16, v102
	v_and_b32_e32 v133, 0xffff0000, v102
	v_lshlrev_b32_e32 v134, 16, v103
	v_and_b32_e32 v135, 0xffff0000, v103
	s_add_i32 s22, s26, s88
	s_add_i32 s22, s22, s88
	s_min_i32 s22, s22, 0x7fff
	s_lshl_b32 s0, s22, 11
	s_add_u32 s0, s4, s0
	s_addc_u32 s1, s5, 0
	global_load_dwordx4 v[96:99], v0, s[0:1]
	global_load_dwordx4 v[100:103], v0, s[0:1] offset:1024
	v_mul_f32_e32 v11, v120, v120
	v_mul_f32_e32 v12, v121, v121
	v_fmac_f32_e32 v11, v122, v122
	v_fmac_f32_e32 v12, v123, v123
	v_fmac_f32_e32 v11, v124, v124
	v_fmac_f32_e32 v12, v125, v125
	v_fmac_f32_e32 v11, v126, v126
	v_fmac_f32_e32 v12, v127, v127
	v_fmac_f32_e32 v11, v128, v128
	v_fmac_f32_e32 v12, v129, v129
	v_fmac_f32_e32 v11, v130, v130
	v_fmac_f32_e32 v12, v131, v131
	v_fmac_f32_e32 v11, v132, v132
	v_fmac_f32_e32 v12, v133, v133
	v_fmac_f32_e32 v11, v134, v134
	v_fmac_f32_e32 v12, v135, v135
	v_add_f32_e32 v11, v11, v12
	ds_bpermute_b32 v12, v2, v11
	s_waitcnt lgkmcnt(0)
	v_add_f32_e32 v11, v11, v12
	ds_bpermute_b32 v12, v3, v11
	s_waitcnt lgkmcnt(0)
	v_add_f32_e32 v11, v11, v12
	ds_bpermute_b32 v12, v5, v11
	s_waitcnt lgkmcnt(0)
	v_add_f32_e32 v11, v11, v12
	ds_bpermute_b32 v12, v7, v11
	s_waitcnt lgkmcnt(0)
	v_add_f32_e32 v11, v11, v12
	ds_bpermute_b32 v12, v8, v11
	s_waitcnt lgkmcnt(0)
	v_add_f32_e32 v11, v11, v12
	ds_bpermute_b32 v12, v9, v11
	s_waitcnt lgkmcnt(0)
; __device__ __forceinline__ unsigned cvt_pk_bf16(float lo, float hi) { unsigned r; asm("v_cvt_pk_bf16_f32 %0, %1, %2" : "=v"(r) : "v"(lo), "v"(hi)); return r; }
; __device__ __forceinline__ void norm_apply(const f32x4 (&v)[4], const float* g, const float* sc, const float* sh, bf16_t* orow, int lane) {
;     float s = 0.f;
; #pragma unroll
;     for (int j = 0; j < 4; ++j) s += (v[j][0] * v[j][0] + v[j][1] * v[j][1]) + (v[j][2] * v[j][2] + v[j][3] * v[j][3]);
;     const float rstd = rsqrtf(wave_sum(s) * (1.f / 1024.f) + EPS);
; #pragma unroll
;     for (int j = 0; j < 4; ++j) { const int c4 = lane + 64 * j;
;         const f32x4 gg = *((const f32x4*)g + c4), cc = *((const f32x4*)sc + c4), hh = *((const f32x4*)sh + c4);
;         const f32x4 h = v[j] * rstd * gg * (cc + 1.f) + hh;
;         u32x2 w; w.x = cvt_pk_bf16(h[0], h[1]); w.y = cvt_pk_bf16(h[2], h[3]);
;         *((u32x2*)orow + c4) = w; }
; __global__ void __launch_bounds__(512, 2) mega_fwd(Args a) {
;     ...
;         for (; row < MP; row += G * 8) {
;             f32x4 v[4];
; #pragma unroll
;             for (int j = 0; j < 4; ++j) v[j] = nv[j];
;             const int nr = row + G * 8;
;             if (nr < MP) row_load_bf16(X1B + (size_t)nr * DM, nv, lane);
;             const int b16 = row >> 12;
;             norm_apply(v, norm2_g, MOD + (size_t)b16 * 6144 + 4096, MOD + (size_t)b16 * 6144 + 3072, Hb + (size_t)row * DM, lane);
	v_add_f32_e32 v11, v11, v12
	v_mov_b32_e32 v12, 0x358637bd
	v_fmac_f32_e32 v12, 0x3a800000, v11
	v_rsq_f32_e32 v13, v12
	s_nop 0
	s_lshl_b32 s12, s26, 11
	s_add_u32 s12, s30, s12
	s_addc_u32 s13, s31, 0
	s_add_u32 s12, s12, 0x1d00000
	s_addc_u32 s13, s13, 0
	v_mul_f32_e32 v120, v13, v120
	v_mul_f32_e32 v121, v13, v121
	v_mul_f32_e32 v122, v13, v122
	v_mul_f32_e32 v123, v13, v123
	v_mul_f32_e32 v124, v13, v124
	v_mul_f32_e32 v125, v13, v125
	v_mul_f32_e32 v126, v13, v126
	v_mul_f32_e32 v127, v13, v127
	v_mul_f32_e32 v128, v13, v128
	v_mul_f32_e32 v129, v13, v129
	v_mul_f32_e32 v130, v13, v130
	v_mul_f32_e32 v131, v13, v131
	v_mul_f32_e32 v132, v13, v132
	v_mul_f32_e32 v133, v13, v133
	v_mul_f32_e32 v134, v13, v134
	v_mul_f32_e32 v135, v13, v135
	v_mul_f32_e32 v120, v16, v120
	v_mul_f32_e32 v121, v17, v121
	v_mul_f32_e32 v122, v18, v122
	v_mul_f32_e32 v123, v19, v123
	v_mul_f32_e32 v124, v20, v124
	v_mul_f32_e32 v125, v21, v125
	v_mul_f32_e32 v126, v22, v126
	v_mul_f32_e32 v127, v23, v127
	v_mul_f32_e32 v128, v24, v128
	v_mul_f32_e32 v129, v25, v129
	v_mul_f32_e32 v130, v26, v130
	v_mul_f32_e32 v131, v27, v131
	v_mul_f32_e32 v132, v28, v132
	v_mul_f32_e32 v133, v29, v133
	v_mul_f32_e32 v134, v30, v134
	v_mul_f32_e32 v135, v31, v135
	v_add_f32_e32 v32, 1.0, v32
	v_add_f32_e32 v33, 1.0, v33
	v_add_f32_e32 v34, 1.0, v34
	v_add_f32_e32 v35, 1.0, v35
	v_add_f32_e32 v36, 1.0, v36
	v_add_f32_e32 v37, 1.0, v37
	v_add_f32_e32 v38, 1.0, v38
	v_add_f32_e32 v39, 1.0, v39
	v_add_f32_e32 v40, 1.0, v40
	v_add_f32_e32 v41, 1.0, v41
	v_add_f32_e32 v42, 1.0, v42
	v_add_f32_e32 v43, 1.0, v43
	v_add_f32_e32 v44, 1.0, v44
	v_add_f32_e32 v45, 1.0, v45
	v_add_f32_e32 v46, 1.0, v46
	v_add_f32_e32 v47, 1.0, v47
	v_fma_f32 v120, v32, v120, v48
	v_fma_f32 v121, v33, v121, v49
	v_fma_f32 v122, v34, v122, v50
	v_fma_f32 v123, v35, v123, v51
	v_fma_f32 v124, v36, v124, v52
	v_fma_f32 v125, v37, v125, v53
	v_fma_f32 v126, v38, v126, v54
	v_fma_f32 v127, v39, v127, v55
	v_fma_f32 v128, v40, v128, v56
	v_fma_f32 v129, v41, v129, v57
	v_fma_f32 v130, v42, v130, v58
	v_fma_f32 v131, v43, v131, v59
	v_fma_f32 v132, v44, v132, v60
	v_fma_f32 v133, v45, v133, v61
	v_fma_f32 v134, v46, v134, v62
	v_fma_f32 v135, v47, v135, v63
	v_cvt_pk_bf16_f32 v120, v120, v121
	v_cvt_pk_bf16_f32 v121, v122, v123
	v_cvt_pk_bf16_f32 v122, v124, v125
	v_cvt_pk_bf16_f32 v123, v126, v127
	v_cvt_pk_bf16_f32 v124, v128, v129
	v_cvt_pk_bf16_f32 v125, v130, v131
	v_cvt_pk_bf16_f32 v126, v132, v133
	v_cvt_pk_bf16_f32 v127, v134, v135
	global_store_dwordx4 v0, v[120:123], s[12:13]
	global_store_dwordx4 v0, v[124:127], s[12:13] offset:1024
	s_add_i32 s26, s26, s88
	s_cmpk_gt_i32 s26, 0x7fff
	s_cbranch_scc1 .Lp6_done
.Lp6_odd:
	s_add_i32 s22, s26, s88
	s_min_i32 s22, s22, 0x7fff
	s_lshr_b32 s23, s22, 12
	s_mul_i32 s23, s23, 0x6000
	s_add_u32 s8, s30, s23
	s_addc_u32 s9, s31, 0
	s_add_u32 s10, s8, 0x4000
	s_addc_u32 s11, s9, 0
	s_add_u32 s8, s8, 0x3000
	s_addc_u32 s9, s9, 0
	global_load_dwordx4 v[32:35], v1, s[10:11]
	global_load_dwordx4 v[36:39], v1, s[10:11] offset:16
	global_load_dwordx4 v[40:43], v1, s[10:11] offset:2048
	global_load_dwordx4 v[44:47], v1, s[10:11] offset:2064
	global_load_dwordx4 v[48:51], v1, s[8:9]
	global_load_dwordx4 v[52:55], v1, s[8:9] offset:16
	global_load_dwordx4 v[56:59], v1, s[8:9] offset:2048
	global_load_dwordx4 v[60:63], v1, s[8:9] offset:2064
	s_waitcnt vmcnt(12)
.Lp6_odd_go:
	v_lshlrev_b32_e32 v120, 16, v104
	v_and_b32_e32 v121, 0xffff0000, v104
	v_lshlrev_b32_e32 v122, 16, v105
	v_and_b32_e32 v123, 0xffff0000, v105
	v_lshlrev_b32_e32 v124, 16, v106
	v_and_b32_e32 v125, 0xffff0000, v106
	v_lshlrev_b32_e32 v126, 16, v107
	v_and_b32_e32 v127, 0xffff0000, v107
	v_lshlrev_b32_e32 v128, 16, v108
	v_and_b32_e32 v129, 0xffff0000, v108
	v_lshlrev_b32_e32 v130, 16, v109
	v_and_b32_e32 v131, 0xffff0000, v109
	v_lshlrev_b32_e32 v132, 16, v110
	v_and_b32_e32 v133, 0xffff0000, v110
	v_lshlrev_b32_e32 v134, 16, v111
	v_and_b32_e32 v135, 0xffff0000, v111
	s_add_i32 s22, s26, s88
	s_add_i32 s22, s22, s88
	s_min_i32 s22, s22, 0x7fff
	s_lshl_b32 s0, s22, 11
	s_add_u32 s0, s4, s0
	s_addc_u32 s1, s5, 0
	global_load_dwordx4 v[104:107], v0, s[0:1]
	global_load_dwordx4 v[108:111], v0, s[0:1] offset:1024
	v_mul_f32_e32 v11, v120, v120
	v_mul_f32_e32 v12, v121, v121
	v_fmac_f32_e32 v11, v122, v122
	v_fmac_f32_e32 v12, v123, v123
	v_fmac_f32_e32 v11, v124, v124
	v_fmac_f32_e32 v12, v125, v125
	v_fmac_f32_e32 v11, v126, v126
	v_fmac_f32_e32 v12, v127, v127
	v_fmac_f32_e32 v11, v128, v128
	v_fmac_f32_e32 v12, v129, v129
	v_fmac_f32_e32 v11, v130, v130
	v_fmac_f32_e32 v12, v131, v131
	v_fmac_f32_e32 v11, v132, v132
	v_fmac_f32_e32 v12, v133, v133
	v_fmac_f32_e32 v11, v134, v134
	v_fmac_f32_e32 v12, v135, v135
	v_add_f32_e32 v11, v11, v12
	ds_bpermute_b32 v12, v2, v11
	s_waitcnt lgkmcnt(0)
	v_add_f32_e32 v11, v11, v12
	ds_bpermute_b32 v12, v3, v11
	s_waitcnt lgkmcnt(0)
	v_add_f32_e32 v11, v11, v12
	ds_bpermute_b32 v12, v5, v11
	s_waitcnt lgkmcnt(0)
	v_add_f32_e32 v11, v11, v12
	ds_bpermute_b32 v12, v7, v11
	s_waitcnt lgkmcnt(0)
	v_add_f32_e32 v11, v11, v12
	ds_bpermute_b32 v12, v8, v11
	s_waitcnt lgkmcnt(0)
	v_add_f32_e32 v11, v11, v12
	ds_bpermute_b32 v12, v9, v11
	s_waitcnt lgkmcnt(0)
; __device__ __forceinline__ unsigned cvt_pk_bf16(float lo, float hi) { unsigned r; asm("v_cvt_pk_bf16_f32 %0, %1, %2" : "=v"(r) : "v"(lo), "v"(hi)); return r; }
; __device__ __forceinline__ void norm_apply(const f32x4 (&v)[4], const float* g, const float* sc, const float* sh, bf16_t* orow, int lane) {
;     float s = 0.f;
; #pragma unroll
;     for (int j = 0; j < 4; ++j) s += (v[j][0] * v[j][0] + v[j][1] * v[j][1]) + (v[j][2] * v[j][2] + v[j][3] * v[j][3]);
;     const float rstd = rsqrtf(wave_sum(s) * (1.f / 1024.f) + EPS);
; #pragma unroll
;     for (int j = 0; j < 4; ++j) { const int c4 = lane + 64 * j;
;         const f32x4 gg = *((const f32x4*)g + c4), cc = *((const f32x4*)sc + c4), hh = *((const f32x4*)sh + c4);
;         const f32x4 h = v[j] * rstd * gg * (cc + 1.f) + hh;
;         u32x2 w; w.x = cvt_pk_bf16(h[0], h[1]); w.y = cvt_pk_bf16(h[2], h[3]);
;         *((u32x2*)orow + c4) = w; }
; __global__ void __launch_bounds__(512, 2) mega_fwd(Args a) {
;     ...
;         for (int sr = ((bx + 128) % G) * 8 + wid; sr < MS; sr += G * 8) { const int b16 = 8 + (sr >> 6); f32x4 v[4];
;             norm_load(x_s + (size_t)sr * DM, v, lane);
;             sample_combine(MOD + (size_t)b16 * 6144 + 2048, PART, 4, sr, v, lane);
;             row_store_bf16(X1B + (size_t)(MP + sr) * DM, v, lane);
	v_add_f32_e32 v11, v11, v12
	v_mov_b32_e32 v12, 0x358637bd
	v_fmac_f32_e32 v12, 0x3a800000, v11
	v_rsq_f32_e32 v13, v12
	s_nop 0
	s_lshl_b32 s12, s26, 11
	s_add_u32 s12, s30, s12
	s_addc_u32 s13, s31, 0
	s_add_u32 s12, s12, 0x1d00000
	s_addc_u32 s13, s13, 0
	v_mul_f32_e32 v120, v13, v120
	v_mul_f32_e32 v121, v13, v121
	v_mul_f32_e32 v122, v13, v122
	v_mul_f32_e32 v123, v13, v123
	v_mul_f32_e32 v124, v13, v124
	v_mul_f32_e32 v125, v13, v125
	v_mul_f32_e32 v126, v13, v126
	v_mul_f32_e32 v127, v13, v127
	v_mul_f32_e32 v128, v13, v128
	v_mul_f32_e32 v129, v13, v129
	v_mul_f32_e32 v130, v13, v130
	v_mul_f32_e32 v131, v13, v131
	v_mul_f32_e32 v132, v13, v132
	v_mul_f32_e32 v133, v13, v133
	v_mul_f32_e32 v134, v13, v134
	v_mul_f32_e32 v135, v13, v135
	v_mul_f32_e32 v120, v16, v120
	v_mul_f32_e32 v121, v17, v121
	v_mul_f32_e32 v122, v18, v122
	v_mul_f32_e32 v123, v19, v123
	v_mul_f32_e32 v124, v20, v124
	v_mul_f32_e32 v125, v21, v125
	v_mul_f32_e32 v126, v22, v126
	v_mul_f32_e32 v127, v23, v127
	v_mul_f32_e32 v128, v24, v128
	v_mul_f32_e32 v129, v25, v129
	v_mul_f32_e32 v130, v26, v130
	v_mul_f32_e32 v131, v27, v131
	v_mul_f32_e32 v132, v28, v132
	v_mul_f32_e32 v133, v29, v133
	v_mul_f32_e32 v134, v30, v134
	v_mul_f32_e32 v135, v31, v135
	v_add_f32_e32 v64, 1.0, v64
	v_add_f32_e32 v65, 1.0, v65
	v_add_f32_e32 v66, 1.0, v66
	v_add_f32_e32 v67, 1.0, v67
	v_add_f32_e32 v68, 1.0, v68
	v_add_f32_e32 v69, 1.0, v69
	v_add_f32_e32 v70, 1.0, v70
	v_add_f32_e32 v71, 1.0, v71
	v_add_f32_e32 v72, 1.0, v72
	v_add_f32_e32 v73, 1.0, v73
	v_add_f32_e32 v74, 1.0, v74
	v_add_f32_e32 v75, 1.0, v75
	v_add_f32_e32 v76, 1.0, v76
	v_add_f32_e32 v77, 1.0, v77
	v_add_f32_e32 v78, 1.0, v78
	v_add_f32_e32 v79, 1.0, v79
	v_fma_f32 v120, v64, v120, v80
	v_fma_f32 v121, v65, v121, v81
	v_fma_f32 v122, v66, v122, v82
	v_fma_f32 v123, v67, v123, v83
	v_fma_f32 v124, v68, v124, v84
	v_fma_f32 v125, v69, v125, v85
	v_fma_f32 v126, v70, v126, v86
	v_fma_f32 v127, v71, v127, v87
	v_fma_f32 v128, v72, v128, v88
	v_fma_f32 v129, v73, v129, v89
	v_fma_f32 v130, v74, v130, v90
	v_fma_f32 v131, v75, v131, v91
	v_fma_f32 v132, v76, v132, v92
	v_fma_f32 v133, v77, v133, v93
	v_fma_f32 v134, v78, v134, v94
	v_fma_f32 v135, v79, v135, v95
	v_cvt_pk_bf16_f32 v120, v120, v121
	v_cvt_pk_bf16_f32 v121, v122, v123
	v_cvt_pk_bf16_f32 v122, v124, v125
	v_cvt_pk_bf16_f32 v123, v126, v127
	v_cvt_pk_bf16_f32 v124, v128, v129
	v_cvt_pk_bf16_f32 v125, v130, v131
	v_cvt_pk_bf16_f32 v126, v132, v133
	v_cvt_pk_bf16_f32 v127, v134, v135
	global_store_dwordx4 v0, v[120:123], s[12:13]
	global_store_dwordx4 v0, v[124:127], s[12:13] offset:1024
	s_add_i32 s26, s26, s88
	s_cmpk_gt_i32 s26, 0x7fff
	s_cbranch_scc1 .Lp6_done
	s_branch .Lp6_even
.Lp6_done:
	s_waitcnt vmcnt(0)
.LBB0_1105:
	s_abs_i32 s0, s34
	v_cvt_f32_u32_e32 v1, s0
	s_sub_i32 s9, 0, s0
	s_add_i32 s1, s2, 0x80
	s_ashr_i32 s8, s1, 31
	v_rcp_iflag_f32_e32 v1, v1
	s_abs_i32 s1, s1
	v_mul_f32_e32 v1, 0x4f7ffffe, v1
	v_cvt_u32_f32_e32 v1, v1
	s_nop 0
	v_readfirstlane_b32 s10, v1
	s_mul_i32 s9, s9, s10
	s_mul_hi_u32 s9, s10, s9
	s_add_i32 s10, s10, s9
	s_mul_hi_u32 s9, s1, s10
	s_mul_i32 s9, s9, s0
	s_sub_i32 s1, s1, s9
	s_sub_i32 s9, s1, s0
	s_cmp_ge_u32 s1, s0
	s_cselect_b32 s1, s9, s1
	s_sub_i32 s9, s1, s0
	s_cmp_ge_u32 s1, s0
	s_cselect_b32 s0, s9, s1
	s_xor_b32 s0, s0, s8
	s_sub_i32 s0, s0, s8
	s_lshl_b32 s0, s0, 3
	s_add_i32 s0, s0, s7
	s_cmpk_gt_i32 s0, 0x1ff
	s_cbranch_scc1 .LBB0_1108
	v_readlane_b32 s8, v238, 20
	v_readlane_b32 s10, v238, 22
	v_readlane_b32 s11, v238, 23
	s_ashr_i32 s1, s0, 31
	s_lshl_b64 s[10:11], s[0:1], 12
	v_mov_b32_e32 v11, 0
	v_readlane_b32 s9, v238, 21
	s_add_u32 s8, s30, s10
	v_readlane_b32 s36, v238, 4
	v_or_b32_e32 v16, 0xc0, v4
	v_mov_b32_e32 v1, v11
	v_readlane_b32 s12, v238, 24
	v_readlane_b32 s13, v238, 25
	v_readlane_b32 s14, v238, 26
	v_readlane_b32 s15, v238, 27
	v_readlane_b32 s18, v238, 30
	v_readlane_b32 s19, v238, 31
	s_addc_u32 s9, s31, s11
	s_ashr_i32 s89, s88, 31
	v_readlane_b32 s38, v238, 6
	v_readlane_b32 s39, v238, 7
	v_readlane_b32 s16, v238, 28
	v_readlane_b32 s17, v238, 29
	v_lshl_add_u64 v[8:9], s[18:19], 0, v[0:1]
	v_readlane_b32 s18, v238, 57
	s_lshl_b64 s[12:13], s[88:89], 12
	s_mov_b64 s[14:15], s[38:39]
	v_lshlrev_b32_e32 v15, 4, v16
	v_mbcnt_hi_u32_b32 v16, -1, v207
	v_or_b32_e32 v14, 0x80, v4
	v_readlane_b32 s21, v238, 33
	v_readlane_b32 s22, v238, 34
	v_readlane_b32 s23, v238, 35
	v_readlane_b32 s16, v238, 55
	v_readlane_b32 s19, v238, 58
	s_add_u32 s14, s14, s10
	v_lshlrev_b32_e32 v12, 4, v4
	v_and_b32_e32 v4, 64, v16
	v_lshl_add_u64 v[2:3], s[4:5], 0, v[10:11]
	v_readlane_b32 s17, v238, 56
	v_lshl_add_u64 v[10:11], s[18:19], 0, v[10:11]
	s_addc_u32 s15, s15, s11
	s_mov_b32 s1, 0x1aa00000
	s_mov_b32 s7, 0x1ac00000
	s_mov_b32 s21, 0x1ae00000
	s_mov_b32 s22, 0x1b000000
	v_lshlrev_b32_e32 v13, 4, v6
	v_lshlrev_b32_e32 v14, 4, v14
	v_add_u32_e32 v17, 64, v4
	v_xor_b32_e32 v18, 1, v16
	v_xor_b32_e32 v19, 2, v16
	v_xor_b32_e32 v20, 4, v16
	v_xor_b32_e32 v21, 8, v16
	v_xor_b32_e32 v22, 16, v16
	v_xor_b32_e32 v23, 32, v16
	v_mov_b32_e32 v24, 0x358637bd
	s_mov_b32 s23, 0x800000
	v_readlane_b32 s20, v238, 32
	v_readlane_b32 s37, v238, 5
	v_readlane_b32 s40, v238, 8
	v_readlane_b32 s41, v238, 9
	v_readlane_b32 s42, v238, 10
	v_readlane_b32 s43, v238, 11
	v_readlane_b32 s44, v238, 12
	v_readlane_b32 s45, v238, 13
	v_readlane_b32 s46, v238, 14
	v_readlane_b32 s47, v238, 15
	v_readlane_b32 s48, v238, 16
	v_readlane_b32 s49, v238, 17
	v_readlane_b32 s50, v238, 18
	v_readlane_b32 s51, v238, 19
